# bias_gemv wave sums via DPP row ops and v_readlane instead of six ds_bpermute hops
# baseline (speedup 1.0000x reference)
.LBB0_182:
	s_waitcnt vmcnt(6)
	v_mbcnt_lo_u32_b32 v0, -1, 0
	v_mbcnt_hi_u32_b32 v5, -1, v0
	v_and_b32_e32 v0, 64, v5
	v_add_u32_e32 v6, 64, v0
	v_xor_b32_e32 v0, 1, v5
	v_cmp_lt_i32_e32 vcc, v0, v6
	v_xor_b32_e32 v1, 2, v5
	v_xor_b32_e32 v9, 32, v5
	v_cndmask_b32_e32 v0, v5, v0, vcc
	v_lshlrev_b32_e32 v0, 2, v0
	v_cmp_lt_i32_e32 vcc, v1, v6
	s_mov_b32 s26, s58
	s_ashr_i32 s27, s58, 31
	v_cndmask_b32_e32 v1, v5, v1, vcc
	v_lshlrev_b32_e32 v1, 2, v1
	s_waitcnt lgkmcnt(0)
	s_nop 1
	v_add_f32_dpp v3, v43, v43 quad_perm:[1,0,3,2] row_mask:0xf bank_mask:0xf
	v_xor_b32_e32 v2, 4, v5
	v_cmp_lt_i32_e32 vcc, v2, v6
	s_lshl_b64 s[26:27], s[26:27], 2
	s_add_u32 s26, s96, s26
	v_cndmask_b32_e32 v2, v5, v2, vcc
	v_lshlrev_b32_e32 v2, 2, v2
	s_waitcnt lgkmcnt(0)
	s_nop 1
	v_add_f32_dpp v4, v3, v3 quad_perm:[2,3,0,1] row_mask:0xf bank_mask:0xf
	v_xor_b32_e32 v3, 8, v5
	v_cmp_lt_i32_e32 vcc, v3, v6
	s_addc_u32 s27, s97, s27
	s_waitcnt lgkmcnt(0)
	s_nop 1
	v_add_f32_dpp v7, v4, v4 row_half_mirror row_mask:0xf bank_mask:0xf
	v_cndmask_b32_e32 v3, v5, v3, vcc
	v_lshlrev_b32_e32 v3, 2, v3
	v_xor_b32_e32 v4, 16, v5
	v_cmp_lt_i32_e32 vcc, v4, v6
	s_waitcnt lgkmcnt(0)
	s_nop 1
	v_add_f32_dpp v7, v7, v7 row_mirror row_mask:0xf bank_mask:0xf
	v_cndmask_b32_e32 v4, v5, v4, vcc
	v_lshlrev_b32_e32 v4, 2, v4
	v_cmp_lt_i32_e32 vcc, v9, v6
	s_waitcnt lgkmcnt(0)
	s_nop 0
	v_readlane_b32 s98, v7, 0
	v_readlane_b32 s99, v7, 16
	v_readlane_b32 s100, v7, 32
	v_readlane_b32 s101, v7, 48
	s_nop 1
	v_mov_b32_e32 v8, s100
	v_add_f32_e32 v8, s101, v8
	v_mov_b32_e32 v6, s98
	v_add_f32_e32 v6, s99, v6
	v_add_f32_e32 v6, v6, v8
	v_cndmask_b32_e32 v5, v5, v9, vcc
	v_lshlrev_b32_e32 v5, 2, v5
	s_and_saveexec_b64 s[28:29], s[0:1]
	s_cbranch_execz .LBB0_184
	s_waitcnt lgkmcnt(0)
	v_mov_b32_e32 v7, 0
	global_store_dword v7, v6, s[26:27]
.LBB0_184:
	s_or_b64 exec, exec, s[28:29]
	s_waitcnt lgkmcnt(0)
	s_nop 1
	v_add_f32_dpp v6, v44, v44 quad_perm:[1,0,3,2] row_mask:0xf bank_mask:0xf
	s_waitcnt lgkmcnt(0)
	s_nop 1
	v_add_f32_dpp v6, v6, v6 quad_perm:[2,3,0,1] row_mask:0xf bank_mask:0xf
	s_waitcnt lgkmcnt(0)
	s_nop 1
	v_add_f32_dpp v6, v6, v6 row_half_mirror row_mask:0xf bank_mask:0xf
	s_waitcnt lgkmcnt(0)
	s_nop 1
	v_add_f32_dpp v6, v6, v6 row_mirror row_mask:0xf bank_mask:0xf
	s_waitcnt lgkmcnt(0)
	s_nop 0
	v_readlane_b32 s98, v6, 0
	v_readlane_b32 s99, v6, 16
	v_readlane_b32 s100, v6, 32
	v_readlane_b32 s101, v6, 48
	s_nop 1
	v_mov_b32_e32 v7, s100
	v_add_f32_e32 v7, s101, v7
	v_mov_b32_e32 v6, s98
	v_add_f32_e32 v6, s99, v6
	v_add_f32_e32 v6, v6, v7
	s_and_saveexec_b64 s[28:29], s[0:1]
	s_cbranch_execz .LBB0_186
	s_waitcnt lgkmcnt(0)
	v_mov_b32_e32 v7, 0xb000
	global_store_dword v7, v6, s[26:27]
.LBB0_186:
	s_or_b64 exec, exec, s[28:29]
	s_waitcnt lgkmcnt(0)
	s_nop 1
	v_add_f32_dpp v6, v45, v45 quad_perm:[1,0,3,2] row_mask:0xf bank_mask:0xf
	s_waitcnt lgkmcnt(0)
	s_nop 1
	v_add_f32_dpp v6, v6, v6 quad_perm:[2,3,0,1] row_mask:0xf bank_mask:0xf
	s_waitcnt lgkmcnt(0)
	s_nop 1
	v_add_f32_dpp v6, v6, v6 row_half_mirror row_mask:0xf bank_mask:0xf
	s_waitcnt lgkmcnt(0)
	s_nop 1
	v_add_f32_dpp v6, v6, v6 row_mirror row_mask:0xf bank_mask:0xf
	s_waitcnt lgkmcnt(0)
	s_nop 0
	v_readlane_b32 s98, v6, 0
	v_readlane_b32 s99, v6, 16
	v_readlane_b32 s100, v6, 32
	v_readlane_b32 s101, v6, 48
	s_nop 1
	v_mov_b32_e32 v7, s100
	v_add_f32_e32 v7, s101, v7
	v_mov_b32_e32 v6, s98
	v_add_f32_e32 v6, s99, v6
	v_add_f32_e32 v6, v6, v7
	s_and_saveexec_b64 s[28:29], s[0:1]
	s_cbranch_execz .LBB0_188
	s_waitcnt lgkmcnt(0)
	v_mov_b32_e32 v7, 0x16000
	global_store_dword v7, v6, s[26:27]
.LBB0_188:
	s_or_b64 exec, exec, s[28:29]
	s_waitcnt lgkmcnt(0)
	s_nop 1
	v_add_f32_dpp v6, v40, v40 quad_perm:[1,0,3,2] row_mask:0xf bank_mask:0xf
	s_waitcnt lgkmcnt(0)
	s_nop 1
	v_add_f32_dpp v6, v6, v6 quad_perm:[2,3,0,1] row_mask:0xf bank_mask:0xf
	s_waitcnt lgkmcnt(0)
	s_nop 1
	v_add_f32_dpp v6, v6, v6 row_half_mirror row_mask:0xf bank_mask:0xf
	s_waitcnt lgkmcnt(0)
	s_nop 1
	v_add_f32_dpp v6, v6, v6 row_mirror row_mask:0xf bank_mask:0xf
	s_waitcnt lgkmcnt(0)
	s_nop 0
	v_readlane_b32 s98, v6, 0
	v_readlane_b32 s99, v6, 16
	v_readlane_b32 s100, v6, 32
	v_readlane_b32 s101, v6, 48
	s_nop 1
	v_mov_b32_e32 v7, s100
	v_add_f32_e32 v7, s101, v7
	v_mov_b32_e32 v6, s98
	v_add_f32_e32 v6, s99, v6
	v_add_f32_e32 v6, v6, v7
	s_and_saveexec_b64 s[28:29], s[0:1]
	s_cbranch_execz .LBB0_190
	s_waitcnt lgkmcnt(0)
	v_mov_b32_e32 v7, 0x21000
	global_store_dword v7, v6, s[26:27]
.LBB0_190:
	s_or_b64 exec, exec, s[28:29]
	s_waitcnt lgkmcnt(0)
	s_nop 1
	v_add_f32_dpp v0, v41, v41 quad_perm:[1,0,3,2] row_mask:0xf bank_mask:0xf
	s_waitcnt lgkmcnt(0)
	s_nop 1
	v_add_f32_dpp v0, v0, v0 quad_perm:[2,3,0,1] row_mask:0xf bank_mask:0xf
	s_waitcnt lgkmcnt(0)
	s_nop 1
	v_add_f32_dpp v0, v0, v0 row_half_mirror row_mask:0xf bank_mask:0xf
	s_waitcnt lgkmcnt(0)
	s_nop 1
	v_add_f32_dpp v0, v0, v0 row_mirror row_mask:0xf bank_mask:0xf
	s_waitcnt lgkmcnt(0)
	s_nop 0
	v_readlane_b32 s98, v0, 0
	v_readlane_b32 s99, v0, 16
	v_readlane_b32 s100, v0, 32
	v_readlane_b32 s101, v0, 48
	s_nop 1
	v_mov_b32_e32 v1, s100
	v_add_f32_e32 v1, s101, v1
	v_mov_b32_e32 v0, s98
	v_add_f32_e32 v0, s99, v0
	v_add_f32_e32 v0, v0, v1
	s_and_saveexec_b64 s[28:29], s[0:1]
	s_cbranch_execz .LBB0_192
	s_waitcnt lgkmcnt(0)
	v_mov_b32_e32 v1, 0x2c000
	global_store_dword v1, v0, s[26:27]

.LBB0_194:
	s_waitcnt vmcnt(6)
	v_mbcnt_lo_u32_b32 v0, -1, 0
	v_mbcnt_hi_u32_b32 v5, -1, v0
	v_and_b32_e32 v0, 64, v5
	v_add_u32_e32 v6, 64, v0
	v_xor_b32_e32 v0, 1, v5
	v_cmp_lt_i32_e32 vcc, v0, v6
	s_waitcnt lgkmcnt(0)
	v_xor_b32_e32 v1, 2, v5
	v_xor_b32_e32 v9, 32, v5
	v_cndmask_b32_e32 v0, v5, v0, vcc
	v_lshlrev_b32_e32 v0, 2, v0
	v_cmp_lt_i32_e32 vcc, v1, v6
	s_ashr_i32 s19, s18, 31
	s_lshl_b64 s[2:3], s[18:19], 2
	v_cndmask_b32_e32 v1, v5, v1, vcc
	v_lshlrev_b32_e32 v1, 2, v1
	s_waitcnt lgkmcnt(0)
	s_nop 1
	v_add_f32_dpp v3, v64, v64 quad_perm:[1,0,3,2] row_mask:0xf bank_mask:0xf
	v_xor_b32_e32 v2, 4, v5
	v_cmp_lt_i32_e32 vcc, v2, v6
	s_add_u32 s2, s96, s2
	s_addc_u32 s3, s97, s3
	v_cndmask_b32_e32 v2, v5, v2, vcc
	v_lshlrev_b32_e32 v2, 2, v2
	s_waitcnt lgkmcnt(0)
	s_nop 1
	v_add_f32_dpp v4, v3, v3 quad_perm:[2,3,0,1] row_mask:0xf bank_mask:0xf
	v_xor_b32_e32 v3, 8, v5
	v_cmp_lt_i32_e32 vcc, v3, v6
	s_waitcnt lgkmcnt(0)
	s_nop 1
	v_add_f32_dpp v7, v4, v4 row_half_mirror row_mask:0xf bank_mask:0xf
	v_cndmask_b32_e32 v3, v5, v3, vcc
	v_lshlrev_b32_e32 v3, 2, v3
	v_xor_b32_e32 v4, 16, v5
	v_cmp_lt_i32_e32 vcc, v4, v6
	s_waitcnt lgkmcnt(0)
	s_nop 1
	v_add_f32_dpp v7, v7, v7 row_mirror row_mask:0xf bank_mask:0xf
	v_cndmask_b32_e32 v4, v5, v4, vcc
	v_lshlrev_b32_e32 v4, 2, v4
	v_cmp_lt_i32_e32 vcc, v9, v6
	s_waitcnt lgkmcnt(0)
	s_nop 0
	v_readlane_b32 s98, v7, 0
	v_readlane_b32 s99, v7, 16
	v_readlane_b32 s100, v7, 32
	v_readlane_b32 s101, v7, 48
	s_nop 1
	v_mov_b32_e32 v8, s100
	v_add_f32_e32 v8, s101, v8
	v_mov_b32_e32 v6, s98
	v_add_f32_e32 v6, s99, v6
	v_add_f32_e32 v6, v6, v8
	v_cndmask_b32_e32 v5, v5, v9, vcc
	v_lshlrev_b32_e32 v5, 2, v5
	s_and_saveexec_b64 s[4:5], s[0:1]
	s_cbranch_execz .LBB0_196
	s_waitcnt lgkmcnt(0)
	v_mov_b32_e32 v7, 0
	global_store_dword v7, v6, s[2:3]
.LBB0_196:
	s_or_b64 exec, exec, s[4:5]
	s_waitcnt lgkmcnt(0)
	s_nop 1
	v_add_f32_dpp v6, v54, v54 quad_perm:[1,0,3,2] row_mask:0xf bank_mask:0xf
	s_waitcnt lgkmcnt(0)
	s_nop 1
	v_add_f32_dpp v6, v6, v6 quad_perm:[2,3,0,1] row_mask:0xf bank_mask:0xf
	s_waitcnt lgkmcnt(0)
	s_nop 1
	v_add_f32_dpp v6, v6, v6 row_half_mirror row_mask:0xf bank_mask:0xf
	s_waitcnt lgkmcnt(0)
	s_nop 1
	v_add_f32_dpp v6, v6, v6 row_mirror row_mask:0xf bank_mask:0xf
	s_waitcnt lgkmcnt(0)
	s_nop 0
	v_readlane_b32 s98, v6, 0
	v_readlane_b32 s99, v6, 16
	v_readlane_b32 s100, v6, 32
	v_readlane_b32 s101, v6, 48
	s_nop 1
	v_mov_b32_e32 v7, s100
	v_add_f32_e32 v7, s101, v7
	v_mov_b32_e32 v6, s98
	v_add_f32_e32 v6, s99, v6
	v_add_f32_e32 v6, v6, v7
	s_and_saveexec_b64 s[4:5], s[0:1]
	s_cbranch_execz .LBB0_198
	s_waitcnt lgkmcnt(0)
	v_mov_b32_e32 v7, 0xb000
	global_store_dword v7, v6, s[2:3]
.LBB0_198:
	s_or_b64 exec, exec, s[4:5]
	s_waitcnt lgkmcnt(0)
	s_nop 1
	v_add_f32_dpp v6, v55, v55 quad_perm:[1,0,3,2] row_mask:0xf bank_mask:0xf
	s_waitcnt lgkmcnt(0)
	s_nop 1
	v_add_f32_dpp v6, v6, v6 quad_perm:[2,3,0,1] row_mask:0xf bank_mask:0xf
	s_waitcnt lgkmcnt(0)
	s_nop 1
	v_add_f32_dpp v6, v6, v6 row_half_mirror row_mask:0xf bank_mask:0xf
	s_waitcnt lgkmcnt(0)
	s_nop 1
	v_add_f32_dpp v6, v6, v6 row_mirror row_mask:0xf bank_mask:0xf
	s_waitcnt lgkmcnt(0)
	s_nop 0
	v_readlane_b32 s98, v6, 0
	v_readlane_b32 s99, v6, 16
	v_readlane_b32 s100, v6, 32
	v_readlane_b32 s101, v6, 48
	s_nop 1
	v_mov_b32_e32 v7, s100
	v_add_f32_e32 v7, s101, v7
	v_mov_b32_e32 v6, s98
	v_add_f32_e32 v6, s99, v6
	v_add_f32_e32 v6, v6, v7
	s_and_saveexec_b64 s[4:5], s[0:1]
	s_cbranch_execz .LBB0_200
	s_waitcnt lgkmcnt(0)
	v_mov_b32_e32 v7, 0x16000
	global_store_dword v7, v6, s[2:3]
.LBB0_200:
	s_or_b64 exec, exec, s[4:5]
	s_waitcnt lgkmcnt(0)
	s_nop 1
	v_add_f32_dpp v6, v48, v48 quad_perm:[1,0,3,2] row_mask:0xf bank_mask:0xf
	s_waitcnt lgkmcnt(0)
	s_nop 1
	v_add_f32_dpp v6, v6, v6 quad_perm:[2,3,0,1] row_mask:0xf bank_mask:0xf
	s_waitcnt lgkmcnt(0)
	s_nop 1
	v_add_f32_dpp v6, v6, v6 row_half_mirror row_mask:0xf bank_mask:0xf
	s_waitcnt lgkmcnt(0)
	s_nop 1
	v_add_f32_dpp v6, v6, v6 row_mirror row_mask:0xf bank_mask:0xf
	s_waitcnt lgkmcnt(0)
	s_nop 0
	v_readlane_b32 s98, v6, 0
	v_readlane_b32 s99, v6, 16
	v_readlane_b32 s100, v6, 32
	v_readlane_b32 s101, v6, 48
	s_nop 1
	v_mov_b32_e32 v7, s100
	v_add_f32_e32 v7, s101, v7
	v_mov_b32_e32 v6, s98
	v_add_f32_e32 v6, s99, v6
	v_add_f32_e32 v6, v6, v7
	s_and_saveexec_b64 s[4:5], s[0:1]
	s_cbranch_execz .LBB0_202
	s_waitcnt lgkmcnt(0)
	v_mov_b32_e32 v7, 0x21000
	global_store_dword v7, v6, s[2:3]
.LBB0_202:
	s_or_b64 exec, exec, s[4:5]
	s_waitcnt lgkmcnt(0)
	s_nop 1
	v_add_f32_dpp v0, v49, v49 quad_perm:[1,0,3,2] row_mask:0xf bank_mask:0xf
	s_waitcnt lgkmcnt(0)
	s_nop 1
	v_add_f32_dpp v0, v0, v0 quad_perm:[2,3,0,1] row_mask:0xf bank_mask:0xf
	s_waitcnt lgkmcnt(0)
	s_nop 1
	v_add_f32_dpp v0, v0, v0 row_half_mirror row_mask:0xf bank_mask:0xf
	s_waitcnt lgkmcnt(0)
	s_nop 1
	v_add_f32_dpp v0, v0, v0 row_mirror row_mask:0xf bank_mask:0xf
	s_waitcnt lgkmcnt(0)
	s_nop 0
	v_readlane_b32 s98, v0, 0
	v_readlane_b32 s99, v0, 16
	v_readlane_b32 s100, v0, 32
	v_readlane_b32 s101, v0, 48
	s_nop 1
	v_mov_b32_e32 v1, s100
	v_add_f32_e32 v1, s101, v1
	v_mov_b32_e32 v0, s98
	v_add_f32_e32 v0, s99, v0
	v_add_f32_e32 v0, v0, v1
	s_and_saveexec_b64 s[4:5], s[0:1]
	s_cbranch_execz .LBB0_204
	s_waitcnt lgkmcnt(0)
	v_mov_b32_e32 v1, 0x2c000
	global_store_dword v1, v0, s[2:3]

.LBB0_206:
	s_waitcnt vmcnt(6)
	v_mbcnt_lo_u32_b32 v0, -1, 0
	v_mbcnt_hi_u32_b32 v5, -1, v0
	v_and_b32_e32 v0, 64, v5
	v_add_u32_e32 v6, 64, v0
	v_xor_b32_e32 v0, 1, v5
	v_cmp_lt_i32_e32 vcc, v0, v6
	s_waitcnt lgkmcnt(0)
	v_xor_b32_e32 v1, 2, v5
	v_xor_b32_e32 v9, 32, v5
	v_cndmask_b32_e32 v0, v5, v0, vcc
	v_lshlrev_b32_e32 v0, 2, v0
	v_cmp_lt_i32_e32 vcc, v1, v6
	s_ashr_i32 s23, s22, 31
	s_lshl_b64 s[2:3], s[22:23], 2
	v_cndmask_b32_e32 v1, v5, v1, vcc
	v_lshlrev_b32_e32 v1, 2, v1
	s_waitcnt lgkmcnt(0)
	s_nop 1
	v_add_f32_dpp v3, v72, v72 quad_perm:[1,0,3,2] row_mask:0xf bank_mask:0xf
	v_xor_b32_e32 v2, 4, v5
	v_cmp_lt_i32_e32 vcc, v2, v6
	s_add_u32 s2, s96, s2
	s_addc_u32 s3, s97, s3
	v_cndmask_b32_e32 v2, v5, v2, vcc
	v_lshlrev_b32_e32 v2, 2, v2
	s_waitcnt lgkmcnt(0)
	s_nop 1
	v_add_f32_dpp v4, v3, v3 quad_perm:[2,3,0,1] row_mask:0xf bank_mask:0xf
	v_xor_b32_e32 v3, 8, v5
	v_cmp_lt_i32_e32 vcc, v3, v6
	s_waitcnt lgkmcnt(0)
	s_nop 1
	v_add_f32_dpp v7, v4, v4 row_half_mirror row_mask:0xf bank_mask:0xf
	v_cndmask_b32_e32 v3, v5, v3, vcc
	v_lshlrev_b32_e32 v3, 2, v3
	v_xor_b32_e32 v4, 16, v5
	v_cmp_lt_i32_e32 vcc, v4, v6
	s_waitcnt lgkmcnt(0)
	s_nop 1
	v_add_f32_dpp v7, v7, v7 row_mirror row_mask:0xf bank_mask:0xf
	v_cndmask_b32_e32 v4, v5, v4, vcc
	v_lshlrev_b32_e32 v4, 2, v4
	v_cmp_lt_i32_e32 vcc, v9, v6
	s_waitcnt lgkmcnt(0)
	s_nop 0
	v_readlane_b32 s98, v7, 0
	v_readlane_b32 s99, v7, 16
	v_readlane_b32 s100, v7, 32
	v_readlane_b32 s101, v7, 48
	s_nop 1
	v_mov_b32_e32 v8, s100
	v_add_f32_e32 v8, s101, v8
	v_mov_b32_e32 v6, s98
	v_add_f32_e32 v6, s99, v6
	v_add_f32_e32 v6, v6, v8
	v_cndmask_b32_e32 v5, v5, v9, vcc
	v_lshlrev_b32_e32 v5, 2, v5
	s_and_saveexec_b64 s[4:5], s[0:1]
	s_cbranch_execz .LBB0_208
	s_waitcnt lgkmcnt(0)
	v_mov_b32_e32 v7, 0
	global_store_dword v7, v6, s[2:3]
.LBB0_208:
	s_or_b64 exec, exec, s[4:5]
	s_waitcnt lgkmcnt(0)
	s_nop 1
	v_add_f32_dpp v6, v66, v66 quad_perm:[1,0,3,2] row_mask:0xf bank_mask:0xf
	s_waitcnt lgkmcnt(0)
	s_nop 1
	v_add_f32_dpp v6, v6, v6 quad_perm:[2,3,0,1] row_mask:0xf bank_mask:0xf
	s_waitcnt lgkmcnt(0)
	s_nop 1
	v_add_f32_dpp v6, v6, v6 row_half_mirror row_mask:0xf bank_mask:0xf
	s_waitcnt lgkmcnt(0)
	s_nop 1
	v_add_f32_dpp v6, v6, v6 row_mirror row_mask:0xf bank_mask:0xf
	s_waitcnt lgkmcnt(0)
	s_nop 0
	v_readlane_b32 s98, v6, 0
	v_readlane_b32 s99, v6, 16
	v_readlane_b32 s100, v6, 32
	v_readlane_b32 s101, v6, 48
	s_nop 1
	v_mov_b32_e32 v7, s100
	v_add_f32_e32 v7, s101, v7
	v_mov_b32_e32 v6, s98
	v_add_f32_e32 v6, s99, v6
	v_add_f32_e32 v6, v6, v7
	s_and_saveexec_b64 s[4:5], s[0:1]
	s_cbranch_execz .LBB0_210
	s_waitcnt lgkmcnt(0)
	v_mov_b32_e32 v7, 0xb000
	global_store_dword v7, v6, s[2:3]
.LBB0_210:
	s_or_b64 exec, exec, s[4:5]
	s_waitcnt lgkmcnt(0)
	s_nop 1
	v_add_f32_dpp v6, v67, v67 quad_perm:[1,0,3,2] row_mask:0xf bank_mask:0xf
	s_waitcnt lgkmcnt(0)
	s_nop 1
	v_add_f32_dpp v6, v6, v6 quad_perm:[2,3,0,1] row_mask:0xf bank_mask:0xf
	s_waitcnt lgkmcnt(0)
	s_nop 1
	v_add_f32_dpp v6, v6, v6 row_half_mirror row_mask:0xf bank_mask:0xf
	s_waitcnt lgkmcnt(0)
	s_nop 1
	v_add_f32_dpp v6, v6, v6 row_mirror row_mask:0xf bank_mask:0xf
	s_waitcnt lgkmcnt(0)
	s_nop 0
	v_readlane_b32 s98, v6, 0
	v_readlane_b32 s99, v6, 16
	v_readlane_b32 s100, v6, 32
	v_readlane_b32 s101, v6, 48
	s_nop 1
	v_mov_b32_e32 v7, s100
	v_add_f32_e32 v7, s101, v7
	v_mov_b32_e32 v6, s98
	v_add_f32_e32 v6, s99, v6
	v_add_f32_e32 v6, v6, v7
	s_and_saveexec_b64 s[4:5], s[0:1]
	s_cbranch_execz .LBB0_212
	s_waitcnt lgkmcnt(0)
	v_mov_b32_e32 v7, 0x16000
	global_store_dword v7, v6, s[2:3]
.LBB0_212:
	s_or_b64 exec, exec, s[4:5]
	s_waitcnt lgkmcnt(0)
	s_nop 1
	v_add_f32_dpp v6, v56, v56 quad_perm:[1,0,3,2] row_mask:0xf bank_mask:0xf
	s_waitcnt lgkmcnt(0)
	s_nop 1
	v_add_f32_dpp v6, v6, v6 quad_perm:[2,3,0,1] row_mask:0xf bank_mask:0xf
	s_waitcnt lgkmcnt(0)
	s_nop 1
	v_add_f32_dpp v6, v6, v6 row_half_mirror row_mask:0xf bank_mask:0xf
	s_waitcnt lgkmcnt(0)
	s_nop 1
	v_add_f32_dpp v6, v6, v6 row_mirror row_mask:0xf bank_mask:0xf
	s_waitcnt lgkmcnt(0)
	s_nop 0
	v_readlane_b32 s98, v6, 0
	v_readlane_b32 s99, v6, 16
	v_readlane_b32 s100, v6, 32
	v_readlane_b32 s101, v6, 48
	s_nop 1
	v_mov_b32_e32 v7, s100
	v_add_f32_e32 v7, s101, v7
	v_mov_b32_e32 v6, s98
	v_add_f32_e32 v6, s99, v6
	v_add_f32_e32 v6, v6, v7
	s_and_saveexec_b64 s[4:5], s[0:1]
	s_cbranch_execz .LBB0_214
	s_waitcnt lgkmcnt(0)
	v_mov_b32_e32 v7, 0x21000
	global_store_dword v7, v6, s[2:3]
.LBB0_214:
	s_or_b64 exec, exec, s[4:5]
	s_waitcnt lgkmcnt(0)
	s_nop 1
	v_add_f32_dpp v0, v57, v57 quad_perm:[1,0,3,2] row_mask:0xf bank_mask:0xf
	s_waitcnt lgkmcnt(0)
	s_nop 1
	v_add_f32_dpp v0, v0, v0 quad_perm:[2,3,0,1] row_mask:0xf bank_mask:0xf
	s_waitcnt lgkmcnt(0)
	s_nop 1
	v_add_f32_dpp v0, v0, v0 row_half_mirror row_mask:0xf bank_mask:0xf
	s_waitcnt lgkmcnt(0)
	s_nop 1
	v_add_f32_dpp v0, v0, v0 row_mirror row_mask:0xf bank_mask:0xf
	s_waitcnt lgkmcnt(0)
	s_nop 0
	v_readlane_b32 s98, v0, 0
	v_readlane_b32 s99, v0, 16
	v_readlane_b32 s100, v0, 32
	v_readlane_b32 s101, v0, 48
	s_nop 1
	v_mov_b32_e32 v1, s100
	v_add_f32_e32 v1, s101, v1
	v_mov_b32_e32 v0, s98
	v_add_f32_e32 v0, s99, v0
	v_add_f32_e32 v0, v0, v1
	s_and_saveexec_b64 s[4:5], s[0:1]
	s_cbranch_execz .LBB0_216
	s_waitcnt lgkmcnt(0)
	v_mov_b32_e32 v1, 0x2c000
	global_store_dword v1, v0, s[2:3]

.LBB0_224:
	s_waitcnt vmcnt(6)
	v_mbcnt_lo_u32_b32 v0, -1, 0
	v_mbcnt_hi_u32_b32 v5, -1, v0
	v_and_b32_e32 v0, 64, v5
	v_add_u32_e32 v6, 64, v0
	v_xor_b32_e32 v0, 1, v5
	v_cmp_lt_i32_e32 vcc, v0, v6
	s_waitcnt lgkmcnt(0)
	v_xor_b32_e32 v1, 2, v5
	v_xor_b32_e32 v9, 32, v5
	v_cndmask_b32_e32 v0, v5, v0, vcc
	v_lshlrev_b32_e32 v0, 2, v0
	v_cmp_lt_i32_e32 vcc, v1, v6
	s_ashr_i32 s17, s16, 31
	s_lshl_b64 s[2:3], s[16:17], 2
	v_cndmask_b32_e32 v1, v5, v1, vcc
	v_lshlrev_b32_e32 v1, 2, v1
	s_waitcnt lgkmcnt(0)
	s_nop 1
	v_add_f32_dpp v3, v58, v58 quad_perm:[1,0,3,2] row_mask:0xf bank_mask:0xf
	v_xor_b32_e32 v2, 4, v5
	v_cmp_lt_i32_e32 vcc, v2, v6
	s_add_u32 s2, s96, s2
	s_addc_u32 s3, s97, s3
	v_cndmask_b32_e32 v2, v5, v2, vcc
	v_lshlrev_b32_e32 v2, 2, v2
	s_waitcnt lgkmcnt(0)
	s_nop 1
	v_add_f32_dpp v4, v3, v3 quad_perm:[2,3,0,1] row_mask:0xf bank_mask:0xf
	v_xor_b32_e32 v3, 8, v5
	v_cmp_lt_i32_e32 vcc, v3, v6
	s_waitcnt lgkmcnt(0)
	s_nop 1
	v_add_f32_dpp v7, v4, v4 row_half_mirror row_mask:0xf bank_mask:0xf
	v_cndmask_b32_e32 v3, v5, v3, vcc
	v_lshlrev_b32_e32 v3, 2, v3
	v_xor_b32_e32 v4, 16, v5
	v_cmp_lt_i32_e32 vcc, v4, v6
	s_waitcnt lgkmcnt(0)
	s_nop 1
	v_add_f32_dpp v7, v7, v7 row_mirror row_mask:0xf bank_mask:0xf
	v_cndmask_b32_e32 v4, v5, v4, vcc
	v_lshlrev_b32_e32 v4, 2, v4
	v_cmp_lt_i32_e32 vcc, v9, v6
	s_waitcnt lgkmcnt(0)
	s_nop 0
	v_readlane_b32 s98, v7, 0
	v_readlane_b32 s99, v7, 16
	v_readlane_b32 s100, v7, 32
	v_readlane_b32 s101, v7, 48
	s_nop 1
	v_mov_b32_e32 v8, s100
	v_add_f32_e32 v8, s101, v8
	v_mov_b32_e32 v6, s98
	v_add_f32_e32 v6, s99, v6
	v_add_f32_e32 v6, v6, v8
	v_cndmask_b32_e32 v5, v5, v9, vcc
	v_lshlrev_b32_e32 v5, 2, v5
	s_and_saveexec_b64 s[16:17], s[0:1]
	s_cbranch_execz .LBB0_226
	s_waitcnt lgkmcnt(0)
	v_mov_b32_e32 v7, 0
	global_store_dword v7, v6, s[2:3]
.LBB0_226:
	s_or_b64 exec, exec, s[16:17]
	s_waitcnt lgkmcnt(0)
	s_nop 1
	v_add_f32_dpp v6, v50, v50 quad_perm:[1,0,3,2] row_mask:0xf bank_mask:0xf
	s_waitcnt lgkmcnt(0)
	s_nop 1
	v_add_f32_dpp v6, v6, v6 quad_perm:[2,3,0,1] row_mask:0xf bank_mask:0xf
	s_waitcnt lgkmcnt(0)
	s_nop 1
	v_add_f32_dpp v6, v6, v6 row_half_mirror row_mask:0xf bank_mask:0xf
	s_waitcnt lgkmcnt(0)
	s_nop 1
	v_add_f32_dpp v6, v6, v6 row_mirror row_mask:0xf bank_mask:0xf
	s_waitcnt lgkmcnt(0)
	s_nop 0
	v_readlane_b32 s98, v6, 0
	v_readlane_b32 s99, v6, 16
	v_readlane_b32 s100, v6, 32
	v_readlane_b32 s101, v6, 48
	s_nop 1
	v_mov_b32_e32 v7, s100
	v_add_f32_e32 v7, s101, v7
	v_mov_b32_e32 v6, s98
	v_add_f32_e32 v6, s99, v6
	v_add_f32_e32 v6, v6, v7
	s_and_saveexec_b64 s[16:17], s[0:1]
	s_cbranch_execz .LBB0_228
	s_waitcnt lgkmcnt(0)
	v_mov_b32_e32 v7, 0xb000
	global_store_dword v7, v6, s[2:3]
.LBB0_228:
	s_or_b64 exec, exec, s[16:17]
	s_waitcnt lgkmcnt(0)
	s_nop 1
	v_add_f32_dpp v6, v51, v51 quad_perm:[1,0,3,2] row_mask:0xf bank_mask:0xf
	s_waitcnt lgkmcnt(0)
	s_nop 1
	v_add_f32_dpp v6, v6, v6 quad_perm:[2,3,0,1] row_mask:0xf bank_mask:0xf
	s_waitcnt lgkmcnt(0)
	s_nop 1
	v_add_f32_dpp v6, v6, v6 row_half_mirror row_mask:0xf bank_mask:0xf
	s_waitcnt lgkmcnt(0)
	s_nop 1
	v_add_f32_dpp v6, v6, v6 row_mirror row_mask:0xf bank_mask:0xf
	s_waitcnt lgkmcnt(0)
	s_nop 0
	v_readlane_b32 s98, v6, 0
	v_readlane_b32 s99, v6, 16
	v_readlane_b32 s100, v6, 32
	v_readlane_b32 s101, v6, 48
	s_nop 1
	v_mov_b32_e32 v7, s100
	v_add_f32_e32 v7, s101, v7
	v_mov_b32_e32 v6, s98
	v_add_f32_e32 v6, s99, v6
	v_add_f32_e32 v6, v6, v7
	s_and_saveexec_b64 s[16:17], s[0:1]
	s_cbranch_execz .LBB0_230
	s_waitcnt lgkmcnt(0)
	v_mov_b32_e32 v7, 0x16000
	global_store_dword v7, v6, s[2:3]
.LBB0_230:
	s_or_b64 exec, exec, s[16:17]
	s_waitcnt lgkmcnt(0)
	s_nop 1
	v_add_f32_dpp v6, v46, v46 quad_perm:[1,0,3,2] row_mask:0xf bank_mask:0xf
	s_waitcnt lgkmcnt(0)
	s_nop 1
	v_add_f32_dpp v6, v6, v6 quad_perm:[2,3,0,1] row_mask:0xf bank_mask:0xf
	s_waitcnt lgkmcnt(0)
	s_nop 1
	v_add_f32_dpp v6, v6, v6 row_half_mirror row_mask:0xf bank_mask:0xf
	s_waitcnt lgkmcnt(0)
	s_nop 1
	v_add_f32_dpp v6, v6, v6 row_mirror row_mask:0xf bank_mask:0xf
	s_waitcnt lgkmcnt(0)
	s_nop 0
	v_readlane_b32 s98, v6, 0
	v_readlane_b32 s99, v6, 16
	v_readlane_b32 s100, v6, 32
	v_readlane_b32 s101, v6, 48
	s_nop 1
	v_mov_b32_e32 v7, s100
	v_add_f32_e32 v7, s101, v7
	v_mov_b32_e32 v6, s98
	v_add_f32_e32 v6, s99, v6
	v_add_f32_e32 v6, v6, v7
	s_and_saveexec_b64 s[16:17], s[0:1]
	s_cbranch_execz .LBB0_232
	s_waitcnt lgkmcnt(0)
	v_mov_b32_e32 v7, 0x21000
	global_store_dword v7, v6, s[2:3]
.LBB0_232:
	s_or_b64 exec, exec, s[16:17]
	s_waitcnt lgkmcnt(0)
	s_nop 1
	v_add_f32_dpp v0, v47, v47 quad_perm:[1,0,3,2] row_mask:0xf bank_mask:0xf
	s_waitcnt lgkmcnt(0)
	s_nop 1
	v_add_f32_dpp v0, v0, v0 quad_perm:[2,3,0,1] row_mask:0xf bank_mask:0xf
	s_waitcnt lgkmcnt(0)
	s_nop 1
	v_add_f32_dpp v0, v0, v0 row_half_mirror row_mask:0xf bank_mask:0xf
	s_waitcnt lgkmcnt(0)
	s_nop 1
	v_add_f32_dpp v0, v0, v0 row_mirror row_mask:0xf bank_mask:0xf
	s_waitcnt lgkmcnt(0)
	s_nop 0
	v_readlane_b32 s98, v0, 0
	v_readlane_b32 s99, v0, 16
	v_readlane_b32 s100, v0, 32
	v_readlane_b32 s101, v0, 48
	s_nop 1
	v_mov_b32_e32 v1, s100
	v_add_f32_e32 v1, s101, v1
	v_mov_b32_e32 v0, s98
	v_add_f32_e32 v0, s99, v0
	v_add_f32_e32 v0, v0, v1
	s_and_saveexec_b64 s[16:17], s[0:1]
	s_cbranch_execz .LBB0_234
	s_waitcnt lgkmcnt(0)
	v_mov_b32_e32 v1, 0x2c000
	global_store_dword v1, v0, s[2:3]

.LBB0_236:
	s_waitcnt vmcnt(6)
	v_mbcnt_lo_u32_b32 v0, -1, 0
	v_mbcnt_hi_u32_b32 v5, -1, v0
	v_and_b32_e32 v0, 64, v5
	v_add_u32_e32 v6, 64, v0
	v_xor_b32_e32 v0, 1, v5
	v_cmp_lt_i32_e32 vcc, v0, v6
	s_waitcnt lgkmcnt(0)
	v_xor_b32_e32 v1, 2, v5
	v_xor_b32_e32 v9, 32, v5
	v_cndmask_b32_e32 v0, v5, v0, vcc
	v_lshlrev_b32_e32 v0, 2, v0
	v_cmp_lt_i32_e32 vcc, v1, v6
	s_ashr_i32 s21, s20, 31
	s_lshl_b64 s[2:3], s[20:21], 2
	v_cndmask_b32_e32 v1, v5, v1, vcc
	v_lshlrev_b32_e32 v1, 2, v1
	s_waitcnt lgkmcnt(0)
	s_nop 1
	v_add_f32_dpp v3, v68, v68 quad_perm:[1,0,3,2] row_mask:0xf bank_mask:0xf
	v_xor_b32_e32 v2, 4, v5
	v_cmp_lt_i32_e32 vcc, v2, v6
	s_add_u32 s2, s96, s2
	s_addc_u32 s3, s97, s3
	v_cndmask_b32_e32 v2, v5, v2, vcc
	v_lshlrev_b32_e32 v2, 2, v2
	s_waitcnt lgkmcnt(0)
	s_nop 1
	v_add_f32_dpp v4, v3, v3 quad_perm:[2,3,0,1] row_mask:0xf bank_mask:0xf
	v_xor_b32_e32 v3, 8, v5
	v_cmp_lt_i32_e32 vcc, v3, v6
	s_waitcnt lgkmcnt(0)
	s_nop 1
	v_add_f32_dpp v7, v4, v4 row_half_mirror row_mask:0xf bank_mask:0xf
	v_cndmask_b32_e32 v3, v5, v3, vcc
	v_lshlrev_b32_e32 v3, 2, v3
	v_xor_b32_e32 v4, 16, v5
	v_cmp_lt_i32_e32 vcc, v4, v6
	s_waitcnt lgkmcnt(0)
	s_nop 1
	v_add_f32_dpp v7, v7, v7 row_mirror row_mask:0xf bank_mask:0xf
	v_cndmask_b32_e32 v4, v5, v4, vcc
	v_lshlrev_b32_e32 v4, 2, v4
	v_cmp_lt_i32_e32 vcc, v9, v6
	s_waitcnt lgkmcnt(0)
	s_nop 0
	v_readlane_b32 s98, v7, 0
	v_readlane_b32 s99, v7, 16
	v_readlane_b32 s100, v7, 32
	v_readlane_b32 s101, v7, 48
	s_nop 1
	v_mov_b32_e32 v8, s100
	v_add_f32_e32 v8, s101, v8
	v_mov_b32_e32 v6, s98
	v_add_f32_e32 v6, s99, v6
	v_add_f32_e32 v6, v6, v8
	v_cndmask_b32_e32 v5, v5, v9, vcc
	v_lshlrev_b32_e32 v5, 2, v5
	s_and_saveexec_b64 s[4:5], s[0:1]
	s_cbranch_execz .LBB0_238
	s_waitcnt lgkmcnt(0)
	v_mov_b32_e32 v7, 0
	global_store_dword v7, v6, s[2:3]
.LBB0_238:
	s_or_b64 exec, exec, s[4:5]
	s_waitcnt lgkmcnt(0)
	s_nop 1
	v_add_f32_dpp v6, v60, v60 quad_perm:[1,0,3,2] row_mask:0xf bank_mask:0xf
	s_waitcnt lgkmcnt(0)
	s_nop 1
	v_add_f32_dpp v6, v6, v6 quad_perm:[2,3,0,1] row_mask:0xf bank_mask:0xf
	s_waitcnt lgkmcnt(0)
	s_nop 1
	v_add_f32_dpp v6, v6, v6 row_half_mirror row_mask:0xf bank_mask:0xf
	s_waitcnt lgkmcnt(0)
	s_nop 1
	v_add_f32_dpp v6, v6, v6 row_mirror row_mask:0xf bank_mask:0xf
	s_waitcnt lgkmcnt(0)
	s_nop 0
	v_readlane_b32 s98, v6, 0
	v_readlane_b32 s99, v6, 16
	v_readlane_b32 s100, v6, 32
	v_readlane_b32 s101, v6, 48
	s_nop 1
	v_mov_b32_e32 v7, s100
	v_add_f32_e32 v7, s101, v7
	v_mov_b32_e32 v6, s98
	v_add_f32_e32 v6, s99, v6
	v_add_f32_e32 v6, v6, v7
	s_and_saveexec_b64 s[4:5], s[0:1]
	s_cbranch_execz .LBB0_240
	s_waitcnt lgkmcnt(0)
	v_mov_b32_e32 v7, 0xb000
	global_store_dword v7, v6, s[2:3]
.LBB0_240:
	s_or_b64 exec, exec, s[4:5]
	s_waitcnt lgkmcnt(0)
	s_nop 1
	v_add_f32_dpp v6, v61, v61 quad_perm:[1,0,3,2] row_mask:0xf bank_mask:0xf
	s_waitcnt lgkmcnt(0)
	s_nop 1
	v_add_f32_dpp v6, v6, v6 quad_perm:[2,3,0,1] row_mask:0xf bank_mask:0xf
	s_waitcnt lgkmcnt(0)
	s_nop 1
	v_add_f32_dpp v6, v6, v6 row_half_mirror row_mask:0xf bank_mask:0xf
	s_waitcnt lgkmcnt(0)
	s_nop 1
	v_add_f32_dpp v6, v6, v6 row_mirror row_mask:0xf bank_mask:0xf
	s_waitcnt lgkmcnt(0)
	s_nop 0
	v_readlane_b32 s98, v6, 0
	v_readlane_b32 s99, v6, 16
	v_readlane_b32 s100, v6, 32
	v_readlane_b32 s101, v6, 48
	s_nop 1
	v_mov_b32_e32 v7, s100
	v_add_f32_e32 v7, s101, v7
	v_mov_b32_e32 v6, s98
	v_add_f32_e32 v6, s99, v6
	v_add_f32_e32 v6, v6, v7
	s_and_saveexec_b64 s[4:5], s[0:1]
	s_cbranch_execz .LBB0_242
	s_waitcnt lgkmcnt(0)
	v_mov_b32_e32 v7, 0x16000
	global_store_dword v7, v6, s[2:3]
.LBB0_242:
	s_or_b64 exec, exec, s[4:5]
	s_waitcnt lgkmcnt(0)
	s_nop 1
	v_add_f32_dpp v6, v52, v52 quad_perm:[1,0,3,2] row_mask:0xf bank_mask:0xf
	s_waitcnt lgkmcnt(0)
	s_nop 1
	v_add_f32_dpp v6, v6, v6 quad_perm:[2,3,0,1] row_mask:0xf bank_mask:0xf
	s_waitcnt lgkmcnt(0)
	s_nop 1
	v_add_f32_dpp v6, v6, v6 row_half_mirror row_mask:0xf bank_mask:0xf
	s_waitcnt lgkmcnt(0)
	s_nop 1
	v_add_f32_dpp v6, v6, v6 row_mirror row_mask:0xf bank_mask:0xf
	s_waitcnt lgkmcnt(0)
	s_nop 0
	v_readlane_b32 s98, v6, 0
	v_readlane_b32 s99, v6, 16
	v_readlane_b32 s100, v6, 32
	v_readlane_b32 s101, v6, 48
	s_nop 1
	v_mov_b32_e32 v7, s100
	v_add_f32_e32 v7, s101, v7
	v_mov_b32_e32 v6, s98
	v_add_f32_e32 v6, s99, v6
	v_add_f32_e32 v6, v6, v7
	s_and_saveexec_b64 s[4:5], s[0:1]
	s_cbranch_execz .LBB0_244
	s_waitcnt lgkmcnt(0)
	v_mov_b32_e32 v7, 0x21000
	global_store_dword v7, v6, s[2:3]
.LBB0_244:
	s_or_b64 exec, exec, s[4:5]
	s_waitcnt lgkmcnt(0)
	s_nop 1
	v_add_f32_dpp v0, v53, v53 quad_perm:[1,0,3,2] row_mask:0xf bank_mask:0xf
	s_waitcnt lgkmcnt(0)
	s_nop 1
	v_add_f32_dpp v0, v0, v0 quad_perm:[2,3,0,1] row_mask:0xf bank_mask:0xf
	s_waitcnt lgkmcnt(0)
	s_nop 1
	v_add_f32_dpp v0, v0, v0 row_half_mirror row_mask:0xf bank_mask:0xf
	s_waitcnt lgkmcnt(0)
	s_nop 1
	v_add_f32_dpp v0, v0, v0 row_mirror row_mask:0xf bank_mask:0xf
	s_waitcnt lgkmcnt(0)
	s_nop 0
	v_readlane_b32 s98, v0, 0
	v_readlane_b32 s99, v0, 16
	v_readlane_b32 s100, v0, 32
	v_readlane_b32 s101, v0, 48
	s_nop 1
	v_mov_b32_e32 v1, s100
	v_add_f32_e32 v1, s101, v1
	v_mov_b32_e32 v0, s98
	v_add_f32_e32 v0, s99, v0
	v_add_f32_e32 v0, v0, v1
	s_and_saveexec_b64 s[4:5], s[0:1]
	s_cbranch_execz .LBB0_246
	s_waitcnt lgkmcnt(0)
	v_mov_b32_e32 v1, 0x2c000
	global_store_dword v1, v0, s[2:3]

.LBB0_248:
	s_waitcnt vmcnt(6)
	v_mbcnt_lo_u32_b32 v0, -1, 0
	v_mbcnt_hi_u32_b32 v5, -1, v0
	v_and_b32_e32 v0, 64, v5
	v_add_u32_e32 v6, 64, v0
	v_xor_b32_e32 v0, 1, v5
	v_cmp_lt_i32_e32 vcc, v0, v6
	s_waitcnt lgkmcnt(0)
	v_xor_b32_e32 v1, 2, v5
	v_xor_b32_e32 v9, 32, v5
	v_cndmask_b32_e32 v0, v5, v0, vcc
	v_lshlrev_b32_e32 v0, 2, v0
	v_cmp_lt_i32_e32 vcc, v1, v6
	s_ashr_i32 s25, s24, 31
	s_lshl_b64 s[2:3], s[24:25], 2
	v_cndmask_b32_e32 v1, v5, v1, vcc
	v_lshlrev_b32_e32 v1, 2, v1
	s_waitcnt lgkmcnt(0)
	s_nop 1
	v_add_f32_dpp v3, v74, v74 quad_perm:[1,0,3,2] row_mask:0xf bank_mask:0xf
	v_xor_b32_e32 v2, 4, v5
	v_cmp_lt_i32_e32 vcc, v2, v6
	s_add_u32 s2, s96, s2
	s_addc_u32 s3, s97, s3
	v_cndmask_b32_e32 v2, v5, v2, vcc
	v_lshlrev_b32_e32 v2, 2, v2
	s_waitcnt lgkmcnt(0)
	s_nop 1
	v_add_f32_dpp v4, v3, v3 quad_perm:[2,3,0,1] row_mask:0xf bank_mask:0xf
	v_xor_b32_e32 v3, 8, v5
	v_cmp_lt_i32_e32 vcc, v3, v6
	s_waitcnt lgkmcnt(0)
	s_nop 1
	v_add_f32_dpp v7, v4, v4 row_half_mirror row_mask:0xf bank_mask:0xf
	v_cndmask_b32_e32 v3, v5, v3, vcc
	v_lshlrev_b32_e32 v3, 2, v3
	v_xor_b32_e32 v4, 16, v5
	v_cmp_lt_i32_e32 vcc, v4, v6
	s_waitcnt lgkmcnt(0)
	s_nop 1
	v_add_f32_dpp v7, v7, v7 row_mirror row_mask:0xf bank_mask:0xf
	v_cndmask_b32_e32 v4, v5, v4, vcc
	v_lshlrev_b32_e32 v4, 2, v4
	v_cmp_lt_i32_e32 vcc, v9, v6
	s_waitcnt lgkmcnt(0)
	s_nop 0
	v_readlane_b32 s98, v7, 0
	v_readlane_b32 s99, v7, 16
	v_readlane_b32 s100, v7, 32
	v_readlane_b32 s101, v7, 48
	s_nop 1
	v_mov_b32_e32 v8, s100
	v_add_f32_e32 v8, s101, v8
	v_mov_b32_e32 v6, s98
	v_add_f32_e32 v6, s99, v6
	v_add_f32_e32 v6, v6, v8
	v_cndmask_b32_e32 v5, v5, v9, vcc
	v_lshlrev_b32_e32 v5, 2, v5
	s_and_saveexec_b64 s[4:5], s[0:1]
	s_cbranch_execz .LBB0_250
	s_waitcnt lgkmcnt(0)
	v_mov_b32_e32 v7, 0
	global_store_dword v7, v6, s[2:3]
.LBB0_250:
	s_or_b64 exec, exec, s[4:5]
	s_waitcnt lgkmcnt(0)
	s_nop 1
	v_add_f32_dpp v6, v70, v70 quad_perm:[1,0,3,2] row_mask:0xf bank_mask:0xf
	s_waitcnt lgkmcnt(0)
	s_nop 1
	v_add_f32_dpp v6, v6, v6 quad_perm:[2,3,0,1] row_mask:0xf bank_mask:0xf
	s_waitcnt lgkmcnt(0)
	s_nop 1
	v_add_f32_dpp v6, v6, v6 row_half_mirror row_mask:0xf bank_mask:0xf
	s_waitcnt lgkmcnt(0)
	s_nop 1
	v_add_f32_dpp v6, v6, v6 row_mirror row_mask:0xf bank_mask:0xf
	s_waitcnt lgkmcnt(0)
	s_nop 0
	v_readlane_b32 s98, v6, 0
	v_readlane_b32 s99, v6, 16
	v_readlane_b32 s100, v6, 32
	v_readlane_b32 s101, v6, 48
	s_nop 1
	v_mov_b32_e32 v7, s100
	v_add_f32_e32 v7, s101, v7
	v_mov_b32_e32 v6, s98
	v_add_f32_e32 v6, s99, v6
	v_add_f32_e32 v6, v6, v7
	s_and_saveexec_b64 s[4:5], s[0:1]
	s_cbranch_execz .LBB0_252
	s_waitcnt lgkmcnt(0)
	v_mov_b32_e32 v7, 0xb000
	global_store_dword v7, v6, s[2:3]
.LBB0_252:
	s_or_b64 exec, exec, s[4:5]
	s_waitcnt lgkmcnt(0)
	s_nop 1
	v_add_f32_dpp v6, v71, v71 quad_perm:[1,0,3,2] row_mask:0xf bank_mask:0xf
	s_waitcnt lgkmcnt(0)
	s_nop 1
	v_add_f32_dpp v6, v6, v6 quad_perm:[2,3,0,1] row_mask:0xf bank_mask:0xf
	s_waitcnt lgkmcnt(0)
	s_nop 1
	v_add_f32_dpp v6, v6, v6 row_half_mirror row_mask:0xf bank_mask:0xf
	s_waitcnt lgkmcnt(0)
	s_nop 1
	v_add_f32_dpp v6, v6, v6 row_mirror row_mask:0xf bank_mask:0xf
	s_waitcnt lgkmcnt(0)
	s_nop 0
	v_readlane_b32 s98, v6, 0
	v_readlane_b32 s99, v6, 16
	v_readlane_b32 s100, v6, 32
	v_readlane_b32 s101, v6, 48
	s_nop 1
	v_mov_b32_e32 v7, s100
	v_add_f32_e32 v7, s101, v7
	v_mov_b32_e32 v6, s98
	v_add_f32_e32 v6, s99, v6
	v_add_f32_e32 v6, v6, v7
	s_and_saveexec_b64 s[4:5], s[0:1]
	s_cbranch_execz .LBB0_254
	s_waitcnt lgkmcnt(0)
	v_mov_b32_e32 v7, 0x16000
	global_store_dword v7, v6, s[2:3]
.LBB0_254:
	s_or_b64 exec, exec, s[4:5]
	s_waitcnt lgkmcnt(0)
	s_nop 1
	v_add_f32_dpp v6, v62, v62 quad_perm:[1,0,3,2] row_mask:0xf bank_mask:0xf
	s_waitcnt lgkmcnt(0)
	s_nop 1
	v_add_f32_dpp v6, v6, v6 quad_perm:[2,3,0,1] row_mask:0xf bank_mask:0xf
	s_waitcnt lgkmcnt(0)
	s_nop 1
	v_add_f32_dpp v6, v6, v6 row_half_mirror row_mask:0xf bank_mask:0xf
	s_waitcnt lgkmcnt(0)
	s_nop 1
	v_add_f32_dpp v6, v6, v6 row_mirror row_mask:0xf bank_mask:0xf
	s_waitcnt lgkmcnt(0)
	s_nop 0
	v_readlane_b32 s98, v6, 0
	v_readlane_b32 s99, v6, 16
	v_readlane_b32 s100, v6, 32
	v_readlane_b32 s101, v6, 48
	s_nop 1
	v_mov_b32_e32 v7, s100
	v_add_f32_e32 v7, s101, v7
	v_mov_b32_e32 v6, s98
	v_add_f32_e32 v6, s99, v6
	v_add_f32_e32 v6, v6, v7
	s_and_saveexec_b64 s[4:5], s[0:1]
	s_cbranch_execz .LBB0_256
	s_waitcnt lgkmcnt(0)
	v_mov_b32_e32 v7, 0x21000
	global_store_dword v7, v6, s[2:3]
.LBB0_256:
	s_or_b64 exec, exec, s[4:5]
	s_waitcnt lgkmcnt(0)
	s_nop 1
	v_add_f32_dpp v0, v63, v63 quad_perm:[1,0,3,2] row_mask:0xf bank_mask:0xf
	s_waitcnt lgkmcnt(0)
	s_nop 1
	v_add_f32_dpp v0, v0, v0 quad_perm:[2,3,0,1] row_mask:0xf bank_mask:0xf
	s_waitcnt lgkmcnt(0)
	s_nop 1
	v_add_f32_dpp v0, v0, v0 row_half_mirror row_mask:0xf bank_mask:0xf
	s_waitcnt lgkmcnt(0)
	s_nop 1
	v_add_f32_dpp v0, v0, v0 row_mirror row_mask:0xf bank_mask:0xf
	s_waitcnt lgkmcnt(0)
	s_nop 0
	v_readlane_b32 s98, v0, 0
	v_readlane_b32 s99, v0, 16
	v_readlane_b32 s100, v0, 32
	v_readlane_b32 s101, v0, 48
	s_nop 1
	v_mov_b32_e32 v1, s100
	v_add_f32_e32 v1, s101, v1
	v_mov_b32_e32 v0, s98
	v_add_f32_e32 v0, s99, v0
	v_add_f32_e32 v0, v0, v1
	s_and_saveexec_b64 s[4:5], s[0:1]
	s_cbranch_execz .LBB0_258
	s_waitcnt lgkmcnt(0)
	v_mov_b32_e32 v1, 0x2c000
	global_store_dword v1, v0, s[2:3]

.LBB0_512:
	s_waitcnt vmcnt(6)
	v_mbcnt_lo_u32_b32 v0, -1, 0
	v_mbcnt_hi_u32_b32 v5, -1, v0
	v_and_b32_e32 v0, 64, v5
	v_add_u32_e32 v6, 64, v0
	v_xor_b32_e32 v0, 1, v5
	v_cmp_lt_i32_e32 vcc, v0, v6
	v_xor_b32_e32 v1, 2, v5
	v_xor_b32_e32 v9, 32, v5
	v_cndmask_b32_e32 v0, v5, v0, vcc
	v_lshlrev_b32_e32 v0, 2, v0
	v_cmp_lt_i32_e32 vcc, v1, v6
	s_ashr_i32 s35, s34, 31
	s_lshl_b64 s[26:27], s[34:35], 2
	v_cndmask_b32_e32 v1, v5, v1, vcc
	v_lshlrev_b32_e32 v1, 2, v1
	s_waitcnt lgkmcnt(0)
	s_nop 1
	v_add_f32_dpp v3, v47, v47 quad_perm:[1,0,3,2] row_mask:0xf bank_mask:0xf
	v_xor_b32_e32 v2, 4, v5
	v_cmp_lt_i32_e32 vcc, v2, v6
	v_readlane_b32 s17, v243, 58
	s_add_u32 s26, s17, s26
	v_cndmask_b32_e32 v2, v5, v2, vcc
	v_lshlrev_b32_e32 v2, 2, v2
	s_waitcnt lgkmcnt(0)
	s_nop 1
	v_add_f32_dpp v4, v3, v3 quad_perm:[2,3,0,1] row_mask:0xf bank_mask:0xf
	v_xor_b32_e32 v3, 8, v5
	v_cmp_lt_i32_e32 vcc, v3, v6
	s_addc_u32 s27, s59, s27
	s_waitcnt lgkmcnt(0)
	s_nop 1
	v_add_f32_dpp v7, v4, v4 row_half_mirror row_mask:0xf bank_mask:0xf
	v_cndmask_b32_e32 v3, v5, v3, vcc
	v_lshlrev_b32_e32 v3, 2, v3
	v_xor_b32_e32 v4, 16, v5
	v_cmp_lt_i32_e32 vcc, v4, v6
	s_waitcnt lgkmcnt(0)
	s_nop 1
	v_add_f32_dpp v7, v7, v7 row_mirror row_mask:0xf bank_mask:0xf
	v_cndmask_b32_e32 v4, v5, v4, vcc
	v_lshlrev_b32_e32 v4, 2, v4
	v_cmp_lt_i32_e32 vcc, v9, v6
	s_waitcnt lgkmcnt(0)
	s_nop 0
	v_readlane_b32 s98, v7, 0
	v_readlane_b32 s99, v7, 16
	v_readlane_b32 s100, v7, 32
	v_readlane_b32 s101, v7, 48
	s_nop 1
	v_mov_b32_e32 v8, s100
	v_add_f32_e32 v8, s101, v8
	v_mov_b32_e32 v6, s98
	v_add_f32_e32 v6, s99, v6
	v_add_f32_e32 v6, v6, v8
	v_cndmask_b32_e32 v5, v5, v9, vcc
	v_lshlrev_b32_e32 v5, 2, v5
	s_and_saveexec_b64 s[28:29], s[0:1]
	s_cbranch_execz .LBB0_514
	s_waitcnt lgkmcnt(0)
	v_mov_b32_e32 v7, 0
	global_store_dword v7, v6, s[26:27]
.LBB0_514:
	s_or_b64 exec, exec, s[28:29]
	s_waitcnt lgkmcnt(0)
	s_nop 1
	v_add_f32_dpp v6, v44, v44 quad_perm:[1,0,3,2] row_mask:0xf bank_mask:0xf
	s_waitcnt lgkmcnt(0)
	s_nop 1
	v_add_f32_dpp v6, v6, v6 quad_perm:[2,3,0,1] row_mask:0xf bank_mask:0xf
	s_waitcnt lgkmcnt(0)
	s_nop 1
	v_add_f32_dpp v6, v6, v6 row_half_mirror row_mask:0xf bank_mask:0xf
	s_waitcnt lgkmcnt(0)
	s_nop 1
	v_add_f32_dpp v6, v6, v6 row_mirror row_mask:0xf bank_mask:0xf
	s_waitcnt lgkmcnt(0)
	s_nop 0
	v_readlane_b32 s98, v6, 0
	v_readlane_b32 s99, v6, 16
	v_readlane_b32 s100, v6, 32
	v_readlane_b32 s101, v6, 48
	s_nop 1
	v_mov_b32_e32 v7, s100
	v_add_f32_e32 v7, s101, v7
	v_mov_b32_e32 v6, s98
	v_add_f32_e32 v6, s99, v6
	v_add_f32_e32 v6, v6, v7
	s_and_saveexec_b64 s[28:29], s[0:1]
	s_cbranch_execz .LBB0_516
	s_waitcnt lgkmcnt(0)
	v_mov_b32_e32 v7, 0x8000
	global_store_dword v7, v6, s[26:27]
.LBB0_516:
	s_or_b64 exec, exec, s[28:29]
	s_waitcnt lgkmcnt(0)
	s_nop 1
	v_add_f32_dpp v6, v45, v45 quad_perm:[1,0,3,2] row_mask:0xf bank_mask:0xf
	s_waitcnt lgkmcnt(0)
	s_nop 1
	v_add_f32_dpp v6, v6, v6 quad_perm:[2,3,0,1] row_mask:0xf bank_mask:0xf
	s_waitcnt lgkmcnt(0)
	s_nop 1
	v_add_f32_dpp v6, v6, v6 row_half_mirror row_mask:0xf bank_mask:0xf
	s_waitcnt lgkmcnt(0)
	s_nop 1
	v_add_f32_dpp v6, v6, v6 row_mirror row_mask:0xf bank_mask:0xf
	s_waitcnt lgkmcnt(0)
	s_nop 0
	v_readlane_b32 s98, v6, 0
	v_readlane_b32 s99, v6, 16
	v_readlane_b32 s100, v6, 32
	v_readlane_b32 s101, v6, 48
	s_nop 1
	v_mov_b32_e32 v7, s100
	v_add_f32_e32 v7, s101, v7
	v_mov_b32_e32 v6, s98
	v_add_f32_e32 v6, s99, v6
	v_add_f32_e32 v6, v6, v7
	s_and_saveexec_b64 s[28:29], s[0:1]
	s_cbranch_execz .LBB0_518
	s_waitcnt lgkmcnt(0)
	v_mov_b32_e32 v7, 0x10000
	global_store_dword v7, v6, s[26:27]
.LBB0_518:
	s_or_b64 exec, exec, s[28:29]
	s_waitcnt lgkmcnt(0)
	s_nop 1
	v_add_f32_dpp v6, v40, v40 quad_perm:[1,0,3,2] row_mask:0xf bank_mask:0xf
	s_waitcnt lgkmcnt(0)
	s_nop 1
	v_add_f32_dpp v6, v6, v6 quad_perm:[2,3,0,1] row_mask:0xf bank_mask:0xf
	s_waitcnt lgkmcnt(0)
	s_nop 1
	v_add_f32_dpp v6, v6, v6 row_half_mirror row_mask:0xf bank_mask:0xf
	s_waitcnt lgkmcnt(0)
	s_nop 1
	v_add_f32_dpp v6, v6, v6 row_mirror row_mask:0xf bank_mask:0xf
	s_waitcnt lgkmcnt(0)
	s_nop 0
	v_readlane_b32 s98, v6, 0
	v_readlane_b32 s99, v6, 16
	v_readlane_b32 s100, v6, 32
	v_readlane_b32 s101, v6, 48
	s_nop 1
	v_mov_b32_e32 v7, s100
	v_add_f32_e32 v7, s101, v7
	v_mov_b32_e32 v6, s98
	v_add_f32_e32 v6, s99, v6
	v_add_f32_e32 v6, v6, v7
	s_and_saveexec_b64 s[28:29], s[0:1]
	s_cbranch_execz .LBB0_520
	s_waitcnt lgkmcnt(0)
	v_mov_b32_e32 v7, 0x18000
	global_store_dword v7, v6, s[26:27]
.LBB0_520:
	s_or_b64 exec, exec, s[28:29]
	s_waitcnt lgkmcnt(0)
	s_nop 1
	v_add_f32_dpp v0, v41, v41 quad_perm:[1,0,3,2] row_mask:0xf bank_mask:0xf
	s_waitcnt lgkmcnt(0)
	s_nop 1
	v_add_f32_dpp v0, v0, v0 quad_perm:[2,3,0,1] row_mask:0xf bank_mask:0xf
	s_waitcnt lgkmcnt(0)
	s_nop 1
	v_add_f32_dpp v0, v0, v0 row_half_mirror row_mask:0xf bank_mask:0xf
	s_waitcnt lgkmcnt(0)
	s_nop 1
	v_add_f32_dpp v0, v0, v0 row_mirror row_mask:0xf bank_mask:0xf
	s_waitcnt lgkmcnt(0)
	s_nop 0
	v_readlane_b32 s98, v0, 0
	v_readlane_b32 s99, v0, 16
	v_readlane_b32 s100, v0, 32
	v_readlane_b32 s101, v0, 48
	s_nop 1
	v_mov_b32_e32 v1, s100
	v_add_f32_e32 v1, s101, v1
	v_mov_b32_e32 v0, s98
	v_add_f32_e32 v0, s99, v0
	v_add_f32_e32 v0, v0, v1
	s_and_saveexec_b64 s[28:29], s[0:1]
	s_cbranch_execz .LBB0_522
	s_waitcnt lgkmcnt(0)
	v_mov_b32_e32 v1, 0x20000
	global_store_dword v1, v0, s[26:27]

.LBB0_524:
	s_waitcnt vmcnt(6)
	v_mbcnt_lo_u32_b32 v0, -1, 0
	v_mbcnt_hi_u32_b32 v5, -1, v0
	v_and_b32_e32 v0, 64, v5
	v_add_u32_e32 v6, 64, v0
	v_xor_b32_e32 v0, 1, v5
	v_cmp_lt_i32_e32 vcc, v0, v6
	s_waitcnt lgkmcnt(0)
	v_xor_b32_e32 v1, 2, v5
	v_xor_b32_e32 v9, 32, v5
	v_cndmask_b32_e32 v0, v5, v0, vcc
	v_lshlrev_b32_e32 v0, 2, v0
	v_cmp_lt_i32_e32 vcc, v1, v6
	s_ashr_i32 s19, s18, 31
	s_lshl_b64 s[2:3], s[18:19], 2
	v_cndmask_b32_e32 v1, v5, v1, vcc
	v_lshlrev_b32_e32 v1, 2, v1
	s_waitcnt lgkmcnt(0)
	s_nop 1
	v_add_f32_dpp v3, v64, v64 quad_perm:[1,0,3,2] row_mask:0xf bank_mask:0xf
	v_xor_b32_e32 v2, 4, v5
	v_cmp_lt_i32_e32 vcc, v2, v6
	v_readlane_b32 s4, v243, 58
	s_add_u32 s2, s4, s2
	v_cndmask_b32_e32 v2, v5, v2, vcc
	v_lshlrev_b32_e32 v2, 2, v2
	s_waitcnt lgkmcnt(0)
	s_nop 1
	v_add_f32_dpp v4, v3, v3 quad_perm:[2,3,0,1] row_mask:0xf bank_mask:0xf
	v_xor_b32_e32 v3, 8, v5
	v_cmp_lt_i32_e32 vcc, v3, v6
	s_addc_u32 s3, s59, s3
	s_waitcnt lgkmcnt(0)
	s_nop 1
	v_add_f32_dpp v7, v4, v4 row_half_mirror row_mask:0xf bank_mask:0xf
	v_cndmask_b32_e32 v3, v5, v3, vcc
	v_lshlrev_b32_e32 v3, 2, v3
	v_xor_b32_e32 v4, 16, v5
	v_cmp_lt_i32_e32 vcc, v4, v6
	s_waitcnt lgkmcnt(0)
	s_nop 1
	v_add_f32_dpp v7, v7, v7 row_mirror row_mask:0xf bank_mask:0xf
	v_cndmask_b32_e32 v4, v5, v4, vcc
	v_lshlrev_b32_e32 v4, 2, v4
	v_cmp_lt_i32_e32 vcc, v9, v6
	s_waitcnt lgkmcnt(0)
	s_nop 0
	v_readlane_b32 s98, v7, 0
	v_readlane_b32 s99, v7, 16
	v_readlane_b32 s100, v7, 32
	v_readlane_b32 s101, v7, 48
	s_nop 1
	v_mov_b32_e32 v8, s100
	v_add_f32_e32 v8, s101, v8
	v_mov_b32_e32 v6, s98
	v_add_f32_e32 v6, s99, v6
	v_add_f32_e32 v6, v6, v8
	v_cndmask_b32_e32 v5, v5, v9, vcc
	v_lshlrev_b32_e32 v5, 2, v5
	s_and_saveexec_b64 s[4:5], s[0:1]
	s_cbranch_execz .LBB0_526
	s_waitcnt lgkmcnt(0)
	v_mov_b32_e32 v7, 0
	global_store_dword v7, v6, s[2:3]
.LBB0_526:
	s_or_b64 exec, exec, s[4:5]
	s_waitcnt lgkmcnt(0)
	s_nop 1
	v_add_f32_dpp v6, v54, v54 quad_perm:[1,0,3,2] row_mask:0xf bank_mask:0xf
	s_waitcnt lgkmcnt(0)
	s_nop 1
	v_add_f32_dpp v6, v6, v6 quad_perm:[2,3,0,1] row_mask:0xf bank_mask:0xf
	s_waitcnt lgkmcnt(0)
	s_nop 1
	v_add_f32_dpp v6, v6, v6 row_half_mirror row_mask:0xf bank_mask:0xf
	s_waitcnt lgkmcnt(0)
	s_nop 1
	v_add_f32_dpp v6, v6, v6 row_mirror row_mask:0xf bank_mask:0xf
	s_waitcnt lgkmcnt(0)
	s_nop 0
	v_readlane_b32 s98, v6, 0
	v_readlane_b32 s99, v6, 16
	v_readlane_b32 s100, v6, 32
	v_readlane_b32 s101, v6, 48
	s_nop 1
	v_mov_b32_e32 v7, s100
	v_add_f32_e32 v7, s101, v7
	v_mov_b32_e32 v6, s98
	v_add_f32_e32 v6, s99, v6
	v_add_f32_e32 v6, v6, v7
	s_and_saveexec_b64 s[4:5], s[0:1]
	s_cbranch_execz .LBB0_528
	s_waitcnt lgkmcnt(0)
	v_mov_b32_e32 v7, 0x8000
	global_store_dword v7, v6, s[2:3]
.LBB0_528:
	s_or_b64 exec, exec, s[4:5]
	s_waitcnt lgkmcnt(0)
	s_nop 1
	v_add_f32_dpp v6, v55, v55 quad_perm:[1,0,3,2] row_mask:0xf bank_mask:0xf
	s_waitcnt lgkmcnt(0)
	s_nop 1
	v_add_f32_dpp v6, v6, v6 quad_perm:[2,3,0,1] row_mask:0xf bank_mask:0xf
	s_waitcnt lgkmcnt(0)
	s_nop 1
	v_add_f32_dpp v6, v6, v6 row_half_mirror row_mask:0xf bank_mask:0xf
	s_waitcnt lgkmcnt(0)
	s_nop 1
	v_add_f32_dpp v6, v6, v6 row_mirror row_mask:0xf bank_mask:0xf
	s_waitcnt lgkmcnt(0)
	s_nop 0
	v_readlane_b32 s98, v6, 0
	v_readlane_b32 s99, v6, 16
	v_readlane_b32 s100, v6, 32
	v_readlane_b32 s101, v6, 48
	s_nop 1
	v_mov_b32_e32 v7, s100
	v_add_f32_e32 v7, s101, v7
	v_mov_b32_e32 v6, s98
	v_add_f32_e32 v6, s99, v6
	v_add_f32_e32 v6, v6, v7
	s_and_saveexec_b64 s[4:5], s[0:1]
	s_cbranch_execz .LBB0_530
	s_waitcnt lgkmcnt(0)
	v_mov_b32_e32 v7, 0x10000
	global_store_dword v7, v6, s[2:3]
.LBB0_530:
	s_or_b64 exec, exec, s[4:5]
	s_waitcnt lgkmcnt(0)
	s_nop 1
	v_add_f32_dpp v6, v48, v48 quad_perm:[1,0,3,2] row_mask:0xf bank_mask:0xf
	s_waitcnt lgkmcnt(0)
	s_nop 1
	v_add_f32_dpp v6, v6, v6 quad_perm:[2,3,0,1] row_mask:0xf bank_mask:0xf
	s_waitcnt lgkmcnt(0)
	s_nop 1
	v_add_f32_dpp v6, v6, v6 row_half_mirror row_mask:0xf bank_mask:0xf
	s_waitcnt lgkmcnt(0)
	s_nop 1
	v_add_f32_dpp v6, v6, v6 row_mirror row_mask:0xf bank_mask:0xf
	s_waitcnt lgkmcnt(0)
	s_nop 0
	v_readlane_b32 s98, v6, 0
	v_readlane_b32 s99, v6, 16
	v_readlane_b32 s100, v6, 32
	v_readlane_b32 s101, v6, 48
	s_nop 1
	v_mov_b32_e32 v7, s100
	v_add_f32_e32 v7, s101, v7
	v_mov_b32_e32 v6, s98
	v_add_f32_e32 v6, s99, v6
	v_add_f32_e32 v6, v6, v7
	s_and_saveexec_b64 s[4:5], s[0:1]
	s_cbranch_execz .LBB0_532
	s_waitcnt lgkmcnt(0)
	v_mov_b32_e32 v7, 0x18000
	global_store_dword v7, v6, s[2:3]
.LBB0_532:
	s_or_b64 exec, exec, s[4:5]
	s_waitcnt lgkmcnt(0)
	s_nop 1
	v_add_f32_dpp v0, v49, v49 quad_perm:[1,0,3,2] row_mask:0xf bank_mask:0xf
	s_waitcnt lgkmcnt(0)
	s_nop 1
	v_add_f32_dpp v0, v0, v0 quad_perm:[2,3,0,1] row_mask:0xf bank_mask:0xf
	s_waitcnt lgkmcnt(0)
	s_nop 1
	v_add_f32_dpp v0, v0, v0 row_half_mirror row_mask:0xf bank_mask:0xf
	s_waitcnt lgkmcnt(0)
	s_nop 1
	v_add_f32_dpp v0, v0, v0 row_mirror row_mask:0xf bank_mask:0xf
	s_waitcnt lgkmcnt(0)
	s_nop 0
	v_readlane_b32 s98, v0, 0
	v_readlane_b32 s99, v0, 16
	v_readlane_b32 s100, v0, 32
	v_readlane_b32 s101, v0, 48
	s_nop 1
	v_mov_b32_e32 v1, s100
	v_add_f32_e32 v1, s101, v1
	v_mov_b32_e32 v0, s98
	v_add_f32_e32 v0, s99, v0
	v_add_f32_e32 v0, v0, v1
	s_and_saveexec_b64 s[4:5], s[0:1]
	s_cbranch_execz .LBB0_534
	s_waitcnt lgkmcnt(0)
	v_mov_b32_e32 v1, 0x20000
	global_store_dword v1, v0, s[2:3]

.LBB0_536:
	s_waitcnt vmcnt(6)
	v_mbcnt_lo_u32_b32 v0, -1, 0
	v_mbcnt_hi_u32_b32 v5, -1, v0
	v_and_b32_e32 v0, 64, v5
	v_add_u32_e32 v6, 64, v0
	v_xor_b32_e32 v0, 1, v5
	v_cmp_lt_i32_e32 vcc, v0, v6
	s_waitcnt lgkmcnt(0)
	v_xor_b32_e32 v1, 2, v5
	v_xor_b32_e32 v9, 32, v5
	v_cndmask_b32_e32 v0, v5, v0, vcc
	v_lshlrev_b32_e32 v0, 2, v0
	v_cmp_lt_i32_e32 vcc, v1, v6
	s_ashr_i32 s23, s22, 31
	s_lshl_b64 s[2:3], s[22:23], 2
	v_cndmask_b32_e32 v1, v5, v1, vcc
	v_lshlrev_b32_e32 v1, 2, v1
	s_waitcnt lgkmcnt(0)
	s_nop 1
	v_add_f32_dpp v3, v72, v72 quad_perm:[1,0,3,2] row_mask:0xf bank_mask:0xf
	v_xor_b32_e32 v2, 4, v5
	v_cmp_lt_i32_e32 vcc, v2, v6
	v_readlane_b32 s4, v243, 58
	s_add_u32 s2, s4, s2
	v_cndmask_b32_e32 v2, v5, v2, vcc
	v_lshlrev_b32_e32 v2, 2, v2
	s_waitcnt lgkmcnt(0)
	s_nop 1
	v_add_f32_dpp v4, v3, v3 quad_perm:[2,3,0,1] row_mask:0xf bank_mask:0xf
	v_xor_b32_e32 v3, 8, v5
	v_cmp_lt_i32_e32 vcc, v3, v6
	s_addc_u32 s3, s59, s3
	s_waitcnt lgkmcnt(0)
	s_nop 1
	v_add_f32_dpp v7, v4, v4 row_half_mirror row_mask:0xf bank_mask:0xf
	v_cndmask_b32_e32 v3, v5, v3, vcc
	v_lshlrev_b32_e32 v3, 2, v3
	v_xor_b32_e32 v4, 16, v5
	v_cmp_lt_i32_e32 vcc, v4, v6
	s_waitcnt lgkmcnt(0)
	s_nop 1
	v_add_f32_dpp v7, v7, v7 row_mirror row_mask:0xf bank_mask:0xf
	v_cndmask_b32_e32 v4, v5, v4, vcc
	v_lshlrev_b32_e32 v4, 2, v4
	v_cmp_lt_i32_e32 vcc, v9, v6
	s_waitcnt lgkmcnt(0)
	s_nop 0
	v_readlane_b32 s98, v7, 0
	v_readlane_b32 s99, v7, 16
	v_readlane_b32 s100, v7, 32
	v_readlane_b32 s101, v7, 48
	s_nop 1
	v_mov_b32_e32 v8, s100
	v_add_f32_e32 v8, s101, v8
	v_mov_b32_e32 v6, s98
	v_add_f32_e32 v6, s99, v6
	v_add_f32_e32 v6, v6, v8
	v_cndmask_b32_e32 v5, v5, v9, vcc
	v_lshlrev_b32_e32 v5, 2, v5
	s_and_saveexec_b64 s[4:5], s[0:1]
	s_cbranch_execz .LBB0_538
	s_waitcnt lgkmcnt(0)
	v_mov_b32_e32 v7, 0
	global_store_dword v7, v6, s[2:3]
.LBB0_538:
	s_or_b64 exec, exec, s[4:5]
	s_waitcnt lgkmcnt(0)
	s_nop 1
	v_add_f32_dpp v6, v66, v66 quad_perm:[1,0,3,2] row_mask:0xf bank_mask:0xf
	s_waitcnt lgkmcnt(0)
	s_nop 1
	v_add_f32_dpp v6, v6, v6 quad_perm:[2,3,0,1] row_mask:0xf bank_mask:0xf
	s_waitcnt lgkmcnt(0)
	s_nop 1
	v_add_f32_dpp v6, v6, v6 row_half_mirror row_mask:0xf bank_mask:0xf
	s_waitcnt lgkmcnt(0)
	s_nop 1
	v_add_f32_dpp v6, v6, v6 row_mirror row_mask:0xf bank_mask:0xf
	s_waitcnt lgkmcnt(0)
	s_nop 0
	v_readlane_b32 s98, v6, 0
	v_readlane_b32 s99, v6, 16
	v_readlane_b32 s100, v6, 32
	v_readlane_b32 s101, v6, 48
	s_nop 1
	v_mov_b32_e32 v7, s100
	v_add_f32_e32 v7, s101, v7
	v_mov_b32_e32 v6, s98
	v_add_f32_e32 v6, s99, v6
	v_add_f32_e32 v6, v6, v7
	s_and_saveexec_b64 s[4:5], s[0:1]
	s_cbranch_execz .LBB0_540
	s_waitcnt lgkmcnt(0)
	v_mov_b32_e32 v7, 0x8000
	global_store_dword v7, v6, s[2:3]
.LBB0_540:
	s_or_b64 exec, exec, s[4:5]
	s_waitcnt lgkmcnt(0)
	s_nop 1
	v_add_f32_dpp v6, v67, v67 quad_perm:[1,0,3,2] row_mask:0xf bank_mask:0xf
	s_waitcnt lgkmcnt(0)
	s_nop 1
	v_add_f32_dpp v6, v6, v6 quad_perm:[2,3,0,1] row_mask:0xf bank_mask:0xf
	s_waitcnt lgkmcnt(0)
	s_nop 1
	v_add_f32_dpp v6, v6, v6 row_half_mirror row_mask:0xf bank_mask:0xf
	s_waitcnt lgkmcnt(0)
	s_nop 1
	v_add_f32_dpp v6, v6, v6 row_mirror row_mask:0xf bank_mask:0xf
	s_waitcnt lgkmcnt(0)
	s_nop 0
	v_readlane_b32 s98, v6, 0
	v_readlane_b32 s99, v6, 16
	v_readlane_b32 s100, v6, 32
	v_readlane_b32 s101, v6, 48
	s_nop 1
	v_mov_b32_e32 v7, s100
	v_add_f32_e32 v7, s101, v7
	v_mov_b32_e32 v6, s98
	v_add_f32_e32 v6, s99, v6
	v_add_f32_e32 v6, v6, v7
	s_and_saveexec_b64 s[4:5], s[0:1]
	s_cbranch_execz .LBB0_542
	s_waitcnt lgkmcnt(0)
	v_mov_b32_e32 v7, 0x10000
	global_store_dword v7, v6, s[2:3]
.LBB0_542:
	s_or_b64 exec, exec, s[4:5]
	s_waitcnt lgkmcnt(0)
	s_nop 1
	v_add_f32_dpp v6, v56, v56 quad_perm:[1,0,3,2] row_mask:0xf bank_mask:0xf
	s_waitcnt lgkmcnt(0)
	s_nop 1
	v_add_f32_dpp v6, v6, v6 quad_perm:[2,3,0,1] row_mask:0xf bank_mask:0xf
	s_waitcnt lgkmcnt(0)
	s_nop 1
	v_add_f32_dpp v6, v6, v6 row_half_mirror row_mask:0xf bank_mask:0xf
	s_waitcnt lgkmcnt(0)
	s_nop 1
	v_add_f32_dpp v6, v6, v6 row_mirror row_mask:0xf bank_mask:0xf
	s_waitcnt lgkmcnt(0)
	s_nop 0
	v_readlane_b32 s98, v6, 0
	v_readlane_b32 s99, v6, 16
	v_readlane_b32 s100, v6, 32
	v_readlane_b32 s101, v6, 48
	s_nop 1
	v_mov_b32_e32 v7, s100
	v_add_f32_e32 v7, s101, v7
	v_mov_b32_e32 v6, s98
	v_add_f32_e32 v6, s99, v6
	v_add_f32_e32 v6, v6, v7
	s_and_saveexec_b64 s[4:5], s[0:1]
	s_cbranch_execz .LBB0_544
	s_waitcnt lgkmcnt(0)
	v_mov_b32_e32 v7, 0x18000
	global_store_dword v7, v6, s[2:3]
.LBB0_544:
	s_or_b64 exec, exec, s[4:5]
	s_waitcnt lgkmcnt(0)
	s_nop 1
	v_add_f32_dpp v0, v57, v57 quad_perm:[1,0,3,2] row_mask:0xf bank_mask:0xf
	s_waitcnt lgkmcnt(0)
	s_nop 1
	v_add_f32_dpp v0, v0, v0 quad_perm:[2,3,0,1] row_mask:0xf bank_mask:0xf
	s_waitcnt lgkmcnt(0)
	s_nop 1
	v_add_f32_dpp v0, v0, v0 row_half_mirror row_mask:0xf bank_mask:0xf
	s_waitcnt lgkmcnt(0)
	s_nop 1
	v_add_f32_dpp v0, v0, v0 row_mirror row_mask:0xf bank_mask:0xf
	s_waitcnt lgkmcnt(0)
	s_nop 0
	v_readlane_b32 s98, v0, 0
	v_readlane_b32 s99, v0, 16
	v_readlane_b32 s100, v0, 32
	v_readlane_b32 s101, v0, 48
	s_nop 1
	v_mov_b32_e32 v1, s100
	v_add_f32_e32 v1, s101, v1
	v_mov_b32_e32 v0, s98
	v_add_f32_e32 v0, s99, v0
	v_add_f32_e32 v0, v0, v1
	s_and_saveexec_b64 s[4:5], s[0:1]
	s_cbranch_execz .LBB0_546
	s_waitcnt lgkmcnt(0)
	v_mov_b32_e32 v1, 0x20000
	global_store_dword v1, v0, s[2:3]

.LBB0_554:
	s_waitcnt vmcnt(6)
	v_mbcnt_lo_u32_b32 v0, -1, 0
	v_mbcnt_hi_u32_b32 v5, -1, v0
	v_and_b32_e32 v0, 64, v5
	v_add_u32_e32 v6, 64, v0
	v_xor_b32_e32 v0, 1, v5
	v_cmp_lt_i32_e32 vcc, v0, v6
	s_waitcnt lgkmcnt(0)
	v_xor_b32_e32 v1, 2, v5
	v_xor_b32_e32 v9, 32, v5
	v_cndmask_b32_e32 v0, v5, v0, vcc
	v_lshlrev_b32_e32 v0, 2, v0
	v_cmp_lt_i32_e32 vcc, v1, v6
	s_ashr_i32 s17, s16, 31
	s_lshl_b64 s[2:3], s[16:17], 2
	v_cndmask_b32_e32 v1, v5, v1, vcc
	v_lshlrev_b32_e32 v1, 2, v1
	s_waitcnt lgkmcnt(0)
	s_nop 1
	v_add_f32_dpp v3, v58, v58 quad_perm:[1,0,3,2] row_mask:0xf bank_mask:0xf
	v_xor_b32_e32 v2, 4, v5
	v_cmp_lt_i32_e32 vcc, v2, v6
	v_readlane_b32 s16, v243, 58
	s_add_u32 s2, s16, s2
	v_cndmask_b32_e32 v2, v5, v2, vcc
	v_lshlrev_b32_e32 v2, 2, v2
	s_waitcnt lgkmcnt(0)
	s_nop 1
	v_add_f32_dpp v4, v3, v3 quad_perm:[2,3,0,1] row_mask:0xf bank_mask:0xf
	v_xor_b32_e32 v3, 8, v5
	v_cmp_lt_i32_e32 vcc, v3, v6
	s_addc_u32 s3, s59, s3
	s_waitcnt lgkmcnt(0)
	s_nop 1
	v_add_f32_dpp v7, v4, v4 row_half_mirror row_mask:0xf bank_mask:0xf
	v_cndmask_b32_e32 v3, v5, v3, vcc
	v_lshlrev_b32_e32 v3, 2, v3
	v_xor_b32_e32 v4, 16, v5
	v_cmp_lt_i32_e32 vcc, v4, v6
	s_waitcnt lgkmcnt(0)
	s_nop 1
	v_add_f32_dpp v7, v7, v7 row_mirror row_mask:0xf bank_mask:0xf
	v_cndmask_b32_e32 v4, v5, v4, vcc
	v_lshlrev_b32_e32 v4, 2, v4
	v_cmp_lt_i32_e32 vcc, v9, v6
	s_waitcnt lgkmcnt(0)
	s_nop 0
	v_readlane_b32 s98, v7, 0
	v_readlane_b32 s99, v7, 16
	v_readlane_b32 s100, v7, 32
	v_readlane_b32 s101, v7, 48
	s_nop 1
	v_mov_b32_e32 v8, s100
	v_add_f32_e32 v8, s101, v8
	v_mov_b32_e32 v6, s98
	v_add_f32_e32 v6, s99, v6
	v_add_f32_e32 v6, v6, v8
	v_cndmask_b32_e32 v5, v5, v9, vcc
	v_lshlrev_b32_e32 v5, 2, v5
	s_and_saveexec_b64 s[16:17], s[0:1]
	s_cbranch_execz .LBB0_556
	s_waitcnt lgkmcnt(0)
	v_mov_b32_e32 v7, 0
	global_store_dword v7, v6, s[2:3]
.LBB0_556:
	s_or_b64 exec, exec, s[16:17]
	s_waitcnt lgkmcnt(0)
	s_nop 1
	v_add_f32_dpp v6, v50, v50 quad_perm:[1,0,3,2] row_mask:0xf bank_mask:0xf
	s_waitcnt lgkmcnt(0)
	s_nop 1
	v_add_f32_dpp v6, v6, v6 quad_perm:[2,3,0,1] row_mask:0xf bank_mask:0xf
	s_waitcnt lgkmcnt(0)
	s_nop 1
	v_add_f32_dpp v6, v6, v6 row_half_mirror row_mask:0xf bank_mask:0xf
	s_waitcnt lgkmcnt(0)
	s_nop 1
	v_add_f32_dpp v6, v6, v6 row_mirror row_mask:0xf bank_mask:0xf
	s_waitcnt lgkmcnt(0)
	s_nop 0
	v_readlane_b32 s98, v6, 0
	v_readlane_b32 s99, v6, 16
	v_readlane_b32 s100, v6, 32
	v_readlane_b32 s101, v6, 48
	s_nop 1
	v_mov_b32_e32 v7, s100
	v_add_f32_e32 v7, s101, v7
	v_mov_b32_e32 v6, s98
	v_add_f32_e32 v6, s99, v6
	v_add_f32_e32 v6, v6, v7
	s_and_saveexec_b64 s[16:17], s[0:1]
	s_cbranch_execz .LBB0_558
	s_waitcnt lgkmcnt(0)
	v_mov_b32_e32 v7, 0x8000
	global_store_dword v7, v6, s[2:3]
.LBB0_558:
	s_or_b64 exec, exec, s[16:17]
	s_waitcnt lgkmcnt(0)
	s_nop 1
	v_add_f32_dpp v6, v51, v51 quad_perm:[1,0,3,2] row_mask:0xf bank_mask:0xf
	s_waitcnt lgkmcnt(0)
	s_nop 1
	v_add_f32_dpp v6, v6, v6 quad_perm:[2,3,0,1] row_mask:0xf bank_mask:0xf
	s_waitcnt lgkmcnt(0)
	s_nop 1
	v_add_f32_dpp v6, v6, v6 row_half_mirror row_mask:0xf bank_mask:0xf
	s_waitcnt lgkmcnt(0)
	s_nop 1
	v_add_f32_dpp v6, v6, v6 row_mirror row_mask:0xf bank_mask:0xf
	s_waitcnt lgkmcnt(0)
	s_nop 0
	v_readlane_b32 s98, v6, 0
	v_readlane_b32 s99, v6, 16
	v_readlane_b32 s100, v6, 32
	v_readlane_b32 s101, v6, 48
	s_nop 1
	v_mov_b32_e32 v7, s100
	v_add_f32_e32 v7, s101, v7
	v_mov_b32_e32 v6, s98
	v_add_f32_e32 v6, s99, v6
	v_add_f32_e32 v6, v6, v7
	s_and_saveexec_b64 s[16:17], s[0:1]
	s_cbranch_execz .LBB0_560
	s_waitcnt lgkmcnt(0)
	v_mov_b32_e32 v7, 0x10000
	global_store_dword v7, v6, s[2:3]
.LBB0_560:
	s_or_b64 exec, exec, s[16:17]
	s_waitcnt lgkmcnt(0)
	s_nop 1
	v_add_f32_dpp v6, v42, v42 quad_perm:[1,0,3,2] row_mask:0xf bank_mask:0xf
	s_waitcnt lgkmcnt(0)
	s_nop 1
	v_add_f32_dpp v6, v6, v6 quad_perm:[2,3,0,1] row_mask:0xf bank_mask:0xf
	s_waitcnt lgkmcnt(0)
	s_nop 1
	v_add_f32_dpp v6, v6, v6 row_half_mirror row_mask:0xf bank_mask:0xf
	s_waitcnt lgkmcnt(0)
	s_nop 1
	v_add_f32_dpp v6, v6, v6 row_mirror row_mask:0xf bank_mask:0xf
	s_waitcnt lgkmcnt(0)
	s_nop 0
	v_readlane_b32 s98, v6, 0
	v_readlane_b32 s99, v6, 16
	v_readlane_b32 s100, v6, 32
	v_readlane_b32 s101, v6, 48
	s_nop 1
	v_mov_b32_e32 v7, s100
	v_add_f32_e32 v7, s101, v7
	v_mov_b32_e32 v6, s98
	v_add_f32_e32 v6, s99, v6
	v_add_f32_e32 v6, v6, v7
	s_and_saveexec_b64 s[16:17], s[0:1]
	s_cbranch_execz .LBB0_562
	s_waitcnt lgkmcnt(0)
	v_mov_b32_e32 v7, 0x18000
	global_store_dword v7, v6, s[2:3]
.LBB0_562:
	s_or_b64 exec, exec, s[16:17]
	s_waitcnt lgkmcnt(0)
	s_nop 1
	v_add_f32_dpp v0, v43, v43 quad_perm:[1,0,3,2] row_mask:0xf bank_mask:0xf
	s_waitcnt lgkmcnt(0)
	s_nop 1
	v_add_f32_dpp v0, v0, v0 quad_perm:[2,3,0,1] row_mask:0xf bank_mask:0xf
	s_waitcnt lgkmcnt(0)
	s_nop 1
	v_add_f32_dpp v0, v0, v0 row_half_mirror row_mask:0xf bank_mask:0xf
	s_waitcnt lgkmcnt(0)
	s_nop 1
	v_add_f32_dpp v0, v0, v0 row_mirror row_mask:0xf bank_mask:0xf
	s_waitcnt lgkmcnt(0)
	s_nop 0
	v_readlane_b32 s98, v0, 0
	v_readlane_b32 s99, v0, 16
	v_readlane_b32 s100, v0, 32
	v_readlane_b32 s101, v0, 48
	s_nop 1
	v_mov_b32_e32 v1, s100
	v_add_f32_e32 v1, s101, v1
	v_mov_b32_e32 v0, s98
	v_add_f32_e32 v0, s99, v0
	v_add_f32_e32 v0, v0, v1
	s_and_saveexec_b64 s[16:17], s[0:1]
	s_cbranch_execz .LBB0_564
	s_waitcnt lgkmcnt(0)
	v_mov_b32_e32 v1, 0x20000
	global_store_dword v1, v0, s[2:3]

.LBB0_566:
	s_waitcnt vmcnt(6)
	v_mbcnt_lo_u32_b32 v0, -1, 0
	v_mbcnt_hi_u32_b32 v5, -1, v0
	v_and_b32_e32 v0, 64, v5
	v_add_u32_e32 v6, 64, v0
	v_xor_b32_e32 v0, 1, v5
	v_cmp_lt_i32_e32 vcc, v0, v6
	s_waitcnt lgkmcnt(0)
	v_xor_b32_e32 v1, 2, v5
	v_xor_b32_e32 v9, 32, v5
	v_cndmask_b32_e32 v0, v5, v0, vcc
	v_lshlrev_b32_e32 v0, 2, v0
	v_cmp_lt_i32_e32 vcc, v1, v6
	s_ashr_i32 s21, s20, 31
	s_lshl_b64 s[2:3], s[20:21], 2
	v_cndmask_b32_e32 v1, v5, v1, vcc
	v_lshlrev_b32_e32 v1, 2, v1
	s_waitcnt lgkmcnt(0)
	s_nop 1
	v_add_f32_dpp v3, v68, v68 quad_perm:[1,0,3,2] row_mask:0xf bank_mask:0xf
	v_xor_b32_e32 v2, 4, v5
	v_cmp_lt_i32_e32 vcc, v2, v6
	v_readlane_b32 s4, v243, 58
	s_add_u32 s2, s4, s2
	v_cndmask_b32_e32 v2, v5, v2, vcc
	v_lshlrev_b32_e32 v2, 2, v2
	s_waitcnt lgkmcnt(0)
	s_nop 1
	v_add_f32_dpp v4, v3, v3 quad_perm:[2,3,0,1] row_mask:0xf bank_mask:0xf
	v_xor_b32_e32 v3, 8, v5
	v_cmp_lt_i32_e32 vcc, v3, v6
	s_addc_u32 s3, s59, s3
	s_waitcnt lgkmcnt(0)
	s_nop 1
	v_add_f32_dpp v7, v4, v4 row_half_mirror row_mask:0xf bank_mask:0xf
	v_cndmask_b32_e32 v3, v5, v3, vcc
	v_lshlrev_b32_e32 v3, 2, v3
	v_xor_b32_e32 v4, 16, v5
	v_cmp_lt_i32_e32 vcc, v4, v6
	s_waitcnt lgkmcnt(0)
	s_nop 1
	v_add_f32_dpp v7, v7, v7 row_mirror row_mask:0xf bank_mask:0xf
	v_cndmask_b32_e32 v4, v5, v4, vcc
	v_lshlrev_b32_e32 v4, 2, v4
	v_cmp_lt_i32_e32 vcc, v9, v6
	s_waitcnt lgkmcnt(0)
	s_nop 0
	v_readlane_b32 s98, v7, 0
	v_readlane_b32 s99, v7, 16
	v_readlane_b32 s100, v7, 32
	v_readlane_b32 s101, v7, 48
	s_nop 1
	v_mov_b32_e32 v8, s100
	v_add_f32_e32 v8, s101, v8
	v_mov_b32_e32 v6, s98
	v_add_f32_e32 v6, s99, v6
	v_add_f32_e32 v6, v6, v8
	v_cndmask_b32_e32 v5, v5, v9, vcc
	v_lshlrev_b32_e32 v5, 2, v5
	s_and_saveexec_b64 s[4:5], s[0:1]
	s_cbranch_execz .LBB0_568
	s_waitcnt lgkmcnt(0)
	v_mov_b32_e32 v7, 0
	global_store_dword v7, v6, s[2:3]
.LBB0_568:
	s_or_b64 exec, exec, s[4:5]
	s_waitcnt lgkmcnt(0)
	s_nop 1
	v_add_f32_dpp v6, v60, v60 quad_perm:[1,0,3,2] row_mask:0xf bank_mask:0xf
	s_waitcnt lgkmcnt(0)
	s_nop 1
	v_add_f32_dpp v6, v6, v6 quad_perm:[2,3,0,1] row_mask:0xf bank_mask:0xf
	s_waitcnt lgkmcnt(0)
	s_nop 1
	v_add_f32_dpp v6, v6, v6 row_half_mirror row_mask:0xf bank_mask:0xf
	s_waitcnt lgkmcnt(0)
	s_nop 1
	v_add_f32_dpp v6, v6, v6 row_mirror row_mask:0xf bank_mask:0xf
	s_waitcnt lgkmcnt(0)
	s_nop 0
	v_readlane_b32 s98, v6, 0
	v_readlane_b32 s99, v6, 16
	v_readlane_b32 s100, v6, 32
	v_readlane_b32 s101, v6, 48
	s_nop 1
	v_mov_b32_e32 v7, s100
	v_add_f32_e32 v7, s101, v7
	v_mov_b32_e32 v6, s98
	v_add_f32_e32 v6, s99, v6
	v_add_f32_e32 v6, v6, v7
	s_and_saveexec_b64 s[4:5], s[0:1]
	s_cbranch_execz .LBB0_570
	s_waitcnt lgkmcnt(0)
	v_mov_b32_e32 v7, 0x8000
	global_store_dword v7, v6, s[2:3]
.LBB0_570:
	s_or_b64 exec, exec, s[4:5]
	s_waitcnt lgkmcnt(0)
	s_nop 1
	v_add_f32_dpp v6, v61, v61 quad_perm:[1,0,3,2] row_mask:0xf bank_mask:0xf
	s_waitcnt lgkmcnt(0)
	s_nop 1
	v_add_f32_dpp v6, v6, v6 quad_perm:[2,3,0,1] row_mask:0xf bank_mask:0xf
	s_waitcnt lgkmcnt(0)
	s_nop 1
	v_add_f32_dpp v6, v6, v6 row_half_mirror row_mask:0xf bank_mask:0xf
	s_waitcnt lgkmcnt(0)
	s_nop 1
	v_add_f32_dpp v6, v6, v6 row_mirror row_mask:0xf bank_mask:0xf
	s_waitcnt lgkmcnt(0)
	s_nop 0
	v_readlane_b32 s98, v6, 0
	v_readlane_b32 s99, v6, 16
	v_readlane_b32 s100, v6, 32
	v_readlane_b32 s101, v6, 48
	s_nop 1
	v_mov_b32_e32 v7, s100
	v_add_f32_e32 v7, s101, v7
	v_mov_b32_e32 v6, s98
	v_add_f32_e32 v6, s99, v6
	v_add_f32_e32 v6, v6, v7
	s_and_saveexec_b64 s[4:5], s[0:1]
	s_cbranch_execz .LBB0_572
	s_waitcnt lgkmcnt(0)
	v_mov_b32_e32 v7, 0x10000
	global_store_dword v7, v6, s[2:3]
.LBB0_572:
	s_or_b64 exec, exec, s[4:5]
	s_waitcnt lgkmcnt(0)
	s_nop 1
	v_add_f32_dpp v6, v52, v52 quad_perm:[1,0,3,2] row_mask:0xf bank_mask:0xf
	s_waitcnt lgkmcnt(0)
	s_nop 1
	v_add_f32_dpp v6, v6, v6 quad_perm:[2,3,0,1] row_mask:0xf bank_mask:0xf
	s_waitcnt lgkmcnt(0)
	s_nop 1
	v_add_f32_dpp v6, v6, v6 row_half_mirror row_mask:0xf bank_mask:0xf
	s_waitcnt lgkmcnt(0)
	s_nop 1
	v_add_f32_dpp v6, v6, v6 row_mirror row_mask:0xf bank_mask:0xf
	s_waitcnt lgkmcnt(0)
	s_nop 0
	v_readlane_b32 s98, v6, 0
	v_readlane_b32 s99, v6, 16
	v_readlane_b32 s100, v6, 32
	v_readlane_b32 s101, v6, 48
	s_nop 1
	v_mov_b32_e32 v7, s100
	v_add_f32_e32 v7, s101, v7
	v_mov_b32_e32 v6, s98
	v_add_f32_e32 v6, s99, v6
	v_add_f32_e32 v6, v6, v7
	s_and_saveexec_b64 s[4:5], s[0:1]
	s_cbranch_execz .LBB0_574
	s_waitcnt lgkmcnt(0)
	v_mov_b32_e32 v7, 0x18000
	global_store_dword v7, v6, s[2:3]
.LBB0_574:
	s_or_b64 exec, exec, s[4:5]
	s_waitcnt lgkmcnt(0)
	s_nop 1
	v_add_f32_dpp v0, v53, v53 quad_perm:[1,0,3,2] row_mask:0xf bank_mask:0xf
	s_waitcnt lgkmcnt(0)
	s_nop 1
	v_add_f32_dpp v0, v0, v0 quad_perm:[2,3,0,1] row_mask:0xf bank_mask:0xf
	s_waitcnt lgkmcnt(0)
	s_nop 1
	v_add_f32_dpp v0, v0, v0 row_half_mirror row_mask:0xf bank_mask:0xf
	s_waitcnt lgkmcnt(0)
	s_nop 1
	v_add_f32_dpp v0, v0, v0 row_mirror row_mask:0xf bank_mask:0xf
	s_waitcnt lgkmcnt(0)
	s_nop 0
	v_readlane_b32 s98, v0, 0
	v_readlane_b32 s99, v0, 16
	v_readlane_b32 s100, v0, 32
	v_readlane_b32 s101, v0, 48
	s_nop 1
	v_mov_b32_e32 v1, s100
	v_add_f32_e32 v1, s101, v1
	v_mov_b32_e32 v0, s98
	v_add_f32_e32 v0, s99, v0
	v_add_f32_e32 v0, v0, v1
	s_and_saveexec_b64 s[4:5], s[0:1]
	s_cbranch_execz .LBB0_576
	s_waitcnt lgkmcnt(0)
	v_mov_b32_e32 v1, 0x20000
	global_store_dword v1, v0, s[2:3]

.LBB0_578:
	s_waitcnt vmcnt(6)
	v_mbcnt_lo_u32_b32 v0, -1, 0
	v_mbcnt_hi_u32_b32 v5, -1, v0
	v_and_b32_e32 v0, 64, v5
	v_add_u32_e32 v6, 64, v0
	v_xor_b32_e32 v0, 1, v5
	v_cmp_lt_i32_e32 vcc, v0, v6
	s_waitcnt lgkmcnt(0)
	v_xor_b32_e32 v1, 2, v5
	v_xor_b32_e32 v9, 32, v5
	v_cndmask_b32_e32 v0, v5, v0, vcc
	v_lshlrev_b32_e32 v0, 2, v0
	v_cmp_lt_i32_e32 vcc, v1, v6
	s_ashr_i32 s25, s24, 31
	s_lshl_b64 s[2:3], s[24:25], 2
	v_cndmask_b32_e32 v1, v5, v1, vcc
	v_lshlrev_b32_e32 v1, 2, v1
	s_waitcnt lgkmcnt(0)
	s_nop 1
	v_add_f32_dpp v3, v74, v74 quad_perm:[1,0,3,2] row_mask:0xf bank_mask:0xf
	v_xor_b32_e32 v2, 4, v5
	v_cmp_lt_i32_e32 vcc, v2, v6
	v_readlane_b32 s4, v243, 58
	s_add_u32 s2, s4, s2
	v_cndmask_b32_e32 v2, v5, v2, vcc
	v_lshlrev_b32_e32 v2, 2, v2
	s_waitcnt lgkmcnt(0)
	s_nop 1
	v_add_f32_dpp v4, v3, v3 quad_perm:[2,3,0,1] row_mask:0xf bank_mask:0xf
	v_xor_b32_e32 v3, 8, v5
	v_cmp_lt_i32_e32 vcc, v3, v6
	s_addc_u32 s3, s59, s3
	s_waitcnt lgkmcnt(0)
	s_nop 1
	v_add_f32_dpp v7, v4, v4 row_half_mirror row_mask:0xf bank_mask:0xf
	v_cndmask_b32_e32 v3, v5, v3, vcc
	v_lshlrev_b32_e32 v3, 2, v3
	v_xor_b32_e32 v4, 16, v5
	v_cmp_lt_i32_e32 vcc, v4, v6
	s_waitcnt lgkmcnt(0)
	s_nop 1
	v_add_f32_dpp v7, v7, v7 row_mirror row_mask:0xf bank_mask:0xf
	v_cndmask_b32_e32 v4, v5, v4, vcc
	v_lshlrev_b32_e32 v4, 2, v4
	v_cmp_lt_i32_e32 vcc, v9, v6
	s_waitcnt lgkmcnt(0)
	s_nop 0
	v_readlane_b32 s98, v7, 0
	v_readlane_b32 s99, v7, 16
	v_readlane_b32 s100, v7, 32
	v_readlane_b32 s101, v7, 48
	s_nop 1
	v_mov_b32_e32 v8, s100
	v_add_f32_e32 v8, s101, v8
	v_mov_b32_e32 v6, s98
	v_add_f32_e32 v6, s99, v6
	v_add_f32_e32 v6, v6, v8
	v_cndmask_b32_e32 v5, v5, v9, vcc
	v_lshlrev_b32_e32 v5, 2, v5
	s_and_saveexec_b64 s[4:5], s[0:1]
	s_cbranch_execz .LBB0_580
	s_waitcnt lgkmcnt(0)
	v_mov_b32_e32 v7, 0
	global_store_dword v7, v6, s[2:3]
.LBB0_580:
	s_or_b64 exec, exec, s[4:5]
	s_waitcnt lgkmcnt(0)
	s_nop 1
	v_add_f32_dpp v6, v70, v70 quad_perm:[1,0,3,2] row_mask:0xf bank_mask:0xf
	s_waitcnt lgkmcnt(0)
	s_nop 1
	v_add_f32_dpp v6, v6, v6 quad_perm:[2,3,0,1] row_mask:0xf bank_mask:0xf
	s_waitcnt lgkmcnt(0)
	s_nop 1
	v_add_f32_dpp v6, v6, v6 row_half_mirror row_mask:0xf bank_mask:0xf
	s_waitcnt lgkmcnt(0)
	s_nop 1
	v_add_f32_dpp v6, v6, v6 row_mirror row_mask:0xf bank_mask:0xf
	s_waitcnt lgkmcnt(0)
	s_nop 0
	v_readlane_b32 s98, v6, 0
	v_readlane_b32 s99, v6, 16
	v_readlane_b32 s100, v6, 32
	v_readlane_b32 s101, v6, 48
	s_nop 1
	v_mov_b32_e32 v7, s100
	v_add_f32_e32 v7, s101, v7
	v_mov_b32_e32 v6, s98
	v_add_f32_e32 v6, s99, v6
	v_add_f32_e32 v6, v6, v7
	s_and_saveexec_b64 s[4:5], s[0:1]
	s_cbranch_execz .LBB0_582
	s_waitcnt lgkmcnt(0)
	v_mov_b32_e32 v7, 0x8000
	global_store_dword v7, v6, s[2:3]
.LBB0_582:
	s_or_b64 exec, exec, s[4:5]
	s_waitcnt lgkmcnt(0)
	s_nop 1
	v_add_f32_dpp v6, v71, v71 quad_perm:[1,0,3,2] row_mask:0xf bank_mask:0xf
	s_waitcnt lgkmcnt(0)
	s_nop 1
	v_add_f32_dpp v6, v6, v6 quad_perm:[2,3,0,1] row_mask:0xf bank_mask:0xf
	s_waitcnt lgkmcnt(0)
	s_nop 1
	v_add_f32_dpp v6, v6, v6 row_half_mirror row_mask:0xf bank_mask:0xf
	s_waitcnt lgkmcnt(0)
	s_nop 1
	v_add_f32_dpp v6, v6, v6 row_mirror row_mask:0xf bank_mask:0xf
	s_waitcnt lgkmcnt(0)
	s_nop 0
	v_readlane_b32 s98, v6, 0
	v_readlane_b32 s99, v6, 16
	v_readlane_b32 s100, v6, 32
	v_readlane_b32 s101, v6, 48
	s_nop 1
	v_mov_b32_e32 v7, s100
	v_add_f32_e32 v7, s101, v7
	v_mov_b32_e32 v6, s98
	v_add_f32_e32 v6, s99, v6
	v_add_f32_e32 v6, v6, v7
	s_and_saveexec_b64 s[4:5], s[0:1]
	s_cbranch_execz .LBB0_584
	s_waitcnt lgkmcnt(0)
	v_mov_b32_e32 v7, 0x10000
	global_store_dword v7, v6, s[2:3]
.LBB0_584:
	s_or_b64 exec, exec, s[4:5]
	s_waitcnt lgkmcnt(0)
	s_nop 1
	v_add_f32_dpp v6, v62, v62 quad_perm:[1,0,3,2] row_mask:0xf bank_mask:0xf
	s_waitcnt lgkmcnt(0)
	s_nop 1
	v_add_f32_dpp v6, v6, v6 quad_perm:[2,3,0,1] row_mask:0xf bank_mask:0xf
	s_waitcnt lgkmcnt(0)
	s_nop 1
	v_add_f32_dpp v6, v6, v6 row_half_mirror row_mask:0xf bank_mask:0xf
	s_waitcnt lgkmcnt(0)
	s_nop 1
	v_add_f32_dpp v6, v6, v6 row_mirror row_mask:0xf bank_mask:0xf
	s_waitcnt lgkmcnt(0)
	s_nop 0
	v_readlane_b32 s98, v6, 0
	v_readlane_b32 s99, v6, 16
	v_readlane_b32 s100, v6, 32
	v_readlane_b32 s101, v6, 48
	s_nop 1
	v_mov_b32_e32 v7, s100
	v_add_f32_e32 v7, s101, v7
	v_mov_b32_e32 v6, s98
	v_add_f32_e32 v6, s99, v6
	v_add_f32_e32 v6, v6, v7
	s_and_saveexec_b64 s[4:5], s[0:1]
	s_cbranch_execz .LBB0_586
	s_waitcnt lgkmcnt(0)
	v_mov_b32_e32 v7, 0x18000
	global_store_dword v7, v6, s[2:3]
.LBB0_586:
	s_or_b64 exec, exec, s[4:5]
	s_waitcnt lgkmcnt(0)
	s_nop 1
	v_add_f32_dpp v0, v63, v63 quad_perm:[1,0,3,2] row_mask:0xf bank_mask:0xf
	s_waitcnt lgkmcnt(0)
	s_nop 1
	v_add_f32_dpp v0, v0, v0 quad_perm:[2,3,0,1] row_mask:0xf bank_mask:0xf
	s_waitcnt lgkmcnt(0)
	s_nop 1
	v_add_f32_dpp v0, v0, v0 row_half_mirror row_mask:0xf bank_mask:0xf
	s_waitcnt lgkmcnt(0)
	s_nop 1
	v_add_f32_dpp v0, v0, v0 row_mirror row_mask:0xf bank_mask:0xf
	s_waitcnt lgkmcnt(0)
	s_nop 0
	v_readlane_b32 s98, v0, 0
	v_readlane_b32 s99, v0, 16
	v_readlane_b32 s100, v0, 32
	v_readlane_b32 s101, v0, 48
	s_nop 1
	v_mov_b32_e32 v1, s100
	v_add_f32_e32 v1, s101, v1
	v_mov_b32_e32 v0, s98
	v_add_f32_e32 v0, s99, v0
	v_add_f32_e32 v0, v0, v1
	s_and_saveexec_b64 s[4:5], s[0:1]
	s_cbranch_execz .LBB0_588
	s_waitcnt lgkmcnt(0)
	v_mov_b32_e32 v1, 0x20000
	global_store_dword v1, v0, s[2:3]

	.amdhsa_kernel _Z6mk_fwd4Args
		.amdhsa_group_segment_fixed_size 0
		.amdhsa_private_segment_fixed_size 0
		.amdhsa_kernarg_size 496
		.amdhsa_user_sgpr_count 2
		.amdhsa_user_sgpr_dispatch_ptr 0
		.amdhsa_user_sgpr_queue_ptr 0
		.amdhsa_user_sgpr_kernarg_segment_ptr 1
		.amdhsa_user_sgpr_dispatch_id 0
		.amdhsa_user_sgpr_kernarg_preload_length 0
		.amdhsa_user_sgpr_kernarg_preload_offset 0
		.amdhsa_user_sgpr_private_segment_size 0
		.amdhsa_uses_dynamic_stack 0
		.amdhsa_enable_private_segment 0
		.amdhsa_system_sgpr_workgroup_id_x 1
		.amdhsa_system_sgpr_workgroup_id_y 0
		.amdhsa_system_sgpr_workgroup_id_z 0
		.amdhsa_system_sgpr_workgroup_info 0
		.amdhsa_system_vgpr_workitem_id 2
		.amdhsa_next_free_vgpr 244
		.amdhsa_next_free_sgpr 102
		.amdhsa_accum_offset 244
		.amdhsa_reserve_vcc 1
		.amdhsa_float_round_mode_32 0
		.amdhsa_float_round_mode_16_64 0
		.amdhsa_float_denorm_mode_32 3
		.amdhsa_float_denorm_mode_16_64 3
		.amdhsa_dx10_clamp 1
		.amdhsa_ieee_mode 1
		.amdhsa_fp16_overflow 0
		.amdhsa_tg_split 0
		.amdhsa_exception_fp_ieee_invalid_op 0
		.amdhsa_exception_fp_denorm_src 0
		.amdhsa_exception_fp_ieee_div_zero 0
		.amdhsa_exception_fp_ieee_overflow 0
		.amdhsa_exception_fp_ieee_underflow 0
		.amdhsa_exception_fp_ieee_inexact 0
		.amdhsa_exception_int_div_zero 0
	.end_amdhsa_kernel

amdhsa.kernels:
  - .agpr_count:     0
    .args:
      - .offset:         0
        .size:           240
        .value_kind:     by_value
      - .offset:         240
        .size:           4
        .value_kind:     hidden_block_count_x
      - .offset:         244
        .size:           4
        .value_kind:     hidden_block_count_y
      - .offset:         248
        .size:           4
        .value_kind:     hidden_block_count_z
      - .offset:         252
        .size:           2
        .value_kind:     hidden_group_size_x
      - .offset:         254
        .size:           2
        .value_kind:     hidden_group_size_y
      - .offset:         256
        .size:           2
        .value_kind:     hidden_group_size_z
      - .offset:         258
        .size:           2
        .value_kind:     hidden_remainder_x
      - .offset:         260
        .size:           2
        .value_kind:     hidden_remainder_y
      - .offset:         262
        .size:           2
        .value_kind:     hidden_remainder_z
      - .offset:         280
        .size:           8
        .value_kind:     hidden_global_offset_x
      - .offset:         288
        .size:           8
        .value_kind:     hidden_global_offset_y
      - .offset:         296
        .size:           8
        .value_kind:     hidden_global_offset_z
      - .offset:         304
        .size:           2
        .value_kind:     hidden_grid_dims
      - .offset:         328
        .size:           8
        .value_kind:     hidden_multigrid_sync_arg
      - .offset:         360
        .size:           4
        .value_kind:     hidden_dynamic_lds_size
    .group_segment_fixed_size: 0
    .kernarg_segment_align: 8
    .kernarg_segment_size: 496
    .language:       OpenCL C
    .language_version:
      - 2
      - 0
    .max_flat_workgroup_size: 512
    .name:           _Z6mk_fwd4Args
    .private_segment_fixed_size: 0
    .sgpr_count:     108
    .sgpr_spill_count: 80
    .symbol:         _Z6mk_fwd4Args.kd
    .uniform_work_group_size: 1
    .uses_dynamic_stack: false
    .vgpr_count:     244
    .vgpr_spill_count: 0
    .wavefront_size: 64
